# LDS-DMA loads of all six GEMM K-loops in scalar-base + 32-bit lane-offset form (no per-load 64-bit VALU add); on top of SSD chunk-loop rewrite and out-proj epilogue
# speedup vs baseline: 1.0203x; 1.0028x over previous
; #define PG8_STAGE(bufoff, gbase, voff) do { _Pragma("unroll") for (int _i = 0; _i < 2; ++_i) \
;         __builtin_amdgcn_global_load_lds((const unsigned*)((const char*)(gbase) + (voff)[_i]), (PG8_LAS unsigned*)(lds + (bufoff) + ldsw + _i * 8192), 16, 0, 0); } while (0)
; #define PG8_LDA(dst, b, h) do { _Pragma("unroll") for (int m = 0; m < 4; ++m) _Pragma("unroll") for (int k = 0; k < 2; ++k) dst[m][k] = *(const PG8_LAS bf16x8*)(lds + PG8_SA(b, h) + aoff + m * 2048 + k * 1024); } while (0)
; #define PG8_LDB(dst, b, h) do { _Pragma("unroll") for (int n = 0; n < 2; ++n) _Pragma("unroll") for (int k = 0; k < 2; ++k) dst[n][k] = *(const PG8_LAS bf16x8*)(lds + PG8_SB(b, h) + boff + n * 2048 + k * 1024); } while (0)
; template <class Epi, class Sched, bool ALIGN_EPI = false, bool SP2 = false>
; __device__ __forceinline__ void gemm_phase(PG8_LAS unsigned char* lds, const Gemm g, const Sched& S, const Epi& E, int wave_s) {
;     ...
;             const bool last = (t == nt - 2);
;             const char* a1 = cA + (size_t)(t + 1) * kstep;
;             const char* a2 = last ? nA : cA + (size_t)(t + 2) * kstep; const char* b2 = last ? nB : cB + (size_t)(t + 2) * kstep;
;             const char* a3 = a2 + kstep; const char* b3 = b2 + kstep;
;             if (last && has_next) S.a_ready(nxt);
;             if constexpr (SP2) {
;             PG8_LDB(B0, 0, 0); PG8_LDB(B1, 0, 1); PG8_SCHED; PG8_LDA(At, 0, 0); PG8_STAGE(PG8_SA(1, 1), a1 + hstepA, voffA);
;             PG8_WAIT_V(8); PG8_WAIT_L(0); PG8_BAR; PG8_MMA(0, 0, At, B0); PG8_MMA(0, 1, At, B1); PG8_BAR; PG8_SCHED;
;             PG8_LDA(At, 0, 1); PG8_STAGE(PG8_SB(0, 0), b2, voffB); PG8_STAGE(PG8_SB(0, 1), b2 + hstepB, voffB); PG8_STAGE(PG8_SA(0, 0), a2, voffA);
;             PG8_WAIT_V(8); PG8_WAIT_L(0); PG8_BAR; PG8_MMA(1, 0, At, B0); PG8_MMA(1, 1, At, B1); PG8_BAR; PG8_SCHED;
;             PG8_LDB(B0, 1, 0); PG8_LDB(B1, 1, 1); PG8_SCHED; PG8_LDA(At, 1, 0); PG8_STAGE(PG8_SA(0, 1), a2 + hstepA, voffA);
;             PG8_WAIT_V(8); PG8_WAIT_L(0); PG8_BAR; PG8_MMA(0, 0, At, B0); PG8_MMA(0, 1, At, B1); PG8_BAR; PG8_SCHED;
;             PG8_LDA(At, 1, 1); PG8_STAGE(PG8_SB(1, 0), b3, voffB); PG8_STAGE(PG8_SB(1, 1), b3 + hstepB, voffB); PG8_STAGE(PG8_SA(1, 0), a3, voffA);
;             PG8_WAIT_V(8); PG8_WAIT_L(0); PG8_BAR; PG8_MMA(1, 0, At, B0); PG8_MMA(1, 1, At, B1); PG8_BAR; PG8_SCHED;
.LBB0_192:
	s_add_u32 s26, s18, 0xfff80080
	s_addc_u32 s27, s19, -1
	s_add_i32 s56, 0, 0x10000
	s_cmp_eq_u32 s55, 28
	s_cselect_b32 s37, s23, s27
	s_cselect_b32 s36, s39, s26
	v_add_u32_e32 v146, s56, v149
	s_cselect_b32 s27, s21, s54
	s_cselect_b32 s26, s52, s53
	s_add_i32 s58, 0, 0x14000
	ds_read_b128 v[142:145], v146
	ds_read_b128 v[152:155], v146 offset:1024
	ds_read_b128 v[156:159], v146 offset:2048
	ds_read_b128 v[160:163], v146 offset:3072
	v_add_u32_e32 v146, s58, v149
	ds_read_b128 v[164:167], v146
	ds_read_b128 v[182:185], v146 offset:1024
	ds_read_b128 v[186:189], v146 offset:2048
	ds_read_b128 v[190:193], v146 offset:3072
	s_add_i32 m0, s45, 0xc000
	ds_read_b128 v[194:197], v151
	ds_read_b128 v[198:201], v151 offset:1024
	ds_read_b128 v[212:215], v151 offset:2048
	ds_read_b128 v[216:219], v151 offset:3072
	ds_read_b128 v[220:223], v151 offset:4096
	ds_read_b128 v[224:227], v151 offset:5120
	ds_read_b128 v[228:231], v151 offset:6144
	ds_read_b128 v[232:235], v151 offset:7168
	global_load_lds_dwordx4 v140, s[18:19]
	s_add_i32 m0, s45, 0xe000
	s_nop 0
	global_load_lds_dwordx4 v138, s[18:19]
	s_waitcnt vmcnt(8)
	s_waitcnt lgkmcnt(0)
	s_barrier
	s_setprio 1
	s_waitcnt lgkmcnt(0)
	v_mfma_f32_16x16x32_bf16 v[72:75], v[142:145], v[194:197], v[72:75]
	v_mfma_f32_16x16x32_bf16 v[68:71], v[156:159], v[194:197], v[68:71]
	v_mfma_f32_16x16x32_bf16 v[64:67], v[142:145], v[212:215], v[64:67]
	v_mfma_f32_16x16x32_bf16 v[60:63], v[156:159], v[212:215], v[60:63]
	v_mfma_f32_16x16x32_bf16 v[56:59], v[142:145], v[220:223], v[56:59]
	v_mfma_f32_16x16x32_bf16 v[52:55], v[156:159], v[220:223], v[52:55]
	v_mfma_f32_16x16x32_bf16 v[48:51], v[142:145], v[228:231], v[48:51]
	v_mfma_f32_16x16x32_bf16 v[44:47], v[156:159], v[228:231], v[44:47]
	v_mfma_f32_16x16x32_bf16 v[72:75], v[152:155], v[198:201], v[72:75]
	v_mfma_f32_16x16x32_bf16 v[68:71], v[160:163], v[198:201], v[68:71]
	v_mfma_f32_16x16x32_bf16 v[64:67], v[152:155], v[216:219], v[64:67]
	v_mfma_f32_16x16x32_bf16 v[60:63], v[160:163], v[216:219], v[60:63]
	v_mfma_f32_16x16x32_bf16 v[56:59], v[152:155], v[224:227], v[56:59]
	v_mfma_f32_16x16x32_bf16 v[52:55], v[160:163], v[224:227], v[52:55]
	v_mfma_f32_16x16x32_bf16 v[48:51], v[152:155], v[232:235], v[48:51]
	v_mfma_f32_16x16x32_bf16 v[44:47], v[160:163], v[232:235], v[44:47]
	s_setprio 0
	s_setprio 1
	v_mfma_f32_16x16x32_bf16 v[128:131], v[164:167], v[194:197], v[128:131]
	v_mfma_f32_16x16x32_bf16 v[124:127], v[186:189], v[194:197], v[124:127]
	v_mfma_f32_16x16x32_bf16 v[120:123], v[164:167], v[212:215], v[120:123]
	v_mfma_f32_16x16x32_bf16 v[116:119], v[186:189], v[212:215], v[116:119]
	v_mfma_f32_16x16x32_bf16 v[112:115], v[164:167], v[220:223], v[112:115]
	v_mfma_f32_16x16x32_bf16 v[108:111], v[186:189], v[220:223], v[108:111]
	v_mfma_f32_16x16x32_bf16 v[104:107], v[164:167], v[228:231], v[104:107]
	v_mfma_f32_16x16x32_bf16 v[100:103], v[186:189], v[228:231], v[100:103]
	v_mfma_f32_16x16x32_bf16 v[128:131], v[182:185], v[198:201], v[128:131]
	v_mfma_f32_16x16x32_bf16 v[124:127], v[190:193], v[198:201], v[124:127]
	v_mfma_f32_16x16x32_bf16 v[120:123], v[182:185], v[216:219], v[120:123]
	v_mfma_f32_16x16x32_bf16 v[116:119], v[190:193], v[216:219], v[116:119]
	v_mfma_f32_16x16x32_bf16 v[112:115], v[182:185], v[224:227], v[112:115]
	v_mfma_f32_16x16x32_bf16 v[108:111], v[190:193], v[224:227], v[108:111]
	v_mfma_f32_16x16x32_bf16 v[104:107], v[182:185], v[232:235], v[104:107]
	v_mfma_f32_16x16x32_bf16 v[100:103], v[190:193], v[232:235], v[100:103]
	s_setprio 0
	s_barrier
	s_add_i32 s56, s56, s44
	s_add_u32 s98, s26, s60
	s_addc_u32 s99, s27, s61
	s_mov_b32 m0, s56
	ds_read_b128 v[194:197], v151 offset:16384
	ds_read_b128 v[198:201], v151 offset:17408
	ds_read_b128 v[212:215], v151 offset:18432
	ds_read_b128 v[216:219], v151 offset:19456
	ds_read_b128 v[220:223], v151 offset:20480
	ds_read_b128 v[224:227], v151 offset:21504
	ds_read_b128 v[228:231], v151 offset:22528
	ds_read_b128 v[232:235], v151 offset:23552
	global_load_lds_dwordx4 v2, s[26:27]
	s_add_i32 m0, s56, 0x2000
	s_add_u32 s56, s26, 0x80000
	s_addc_u32 s57, s27, 0
	s_add_i32 s58, s58, s44
	global_load_lds_dwordx4 v0, s[26:27]
	s_mov_b32 m0, s58
	s_nop 0
	global_load_lds_dwordx4 v2, s[56:57]
	s_add_i32 m0, s58, 0x2000
	s_nop 0
	global_load_lds_dwordx4 v0, s[56:57]
	s_mov_b32 m0, s45
	s_nop 0
	global_load_lds_dwordx4 v134, s[36:37]
	s_mov_b32 m0, s46
	s_nop 0
	global_load_lds_dwordx4 v132, s[36:37]
	s_waitcnt vmcnt(8)
	s_waitcnt lgkmcnt(0)
	s_barrier
	s_setprio 1
	s_waitcnt lgkmcnt(0)
	v_mfma_f32_16x16x32_bf16 v[32:35], v[142:145], v[194:197], v[32:35]
	v_mfma_f32_16x16x32_bf16 v[28:31], v[156:159], v[194:197], v[28:31]
	v_mfma_f32_16x16x32_bf16 v[24:27], v[142:145], v[212:215], v[24:27]
	v_mfma_f32_16x16x32_bf16 v[20:23], v[156:159], v[212:215], v[20:23]
	v_mfma_f32_16x16x32_bf16 v[16:19], v[142:145], v[220:223], v[16:19]
	v_mfma_f32_16x16x32_bf16 v[12:15], v[156:159], v[220:223], v[12:15]
	v_mfma_f32_16x16x32_bf16 v[8:11], v[142:145], v[228:231], v[8:11]
	v_mfma_f32_16x16x32_bf16 v[4:7], v[156:159], v[228:231], v[4:7]
	v_mfma_f32_16x16x32_bf16 v[32:35], v[152:155], v[198:201], v[32:35]
	v_mfma_f32_16x16x32_bf16 v[28:31], v[160:163], v[198:201], v[28:31]
	v_mfma_f32_16x16x32_bf16 v[24:27], v[152:155], v[216:219], v[24:27]
	v_mfma_f32_16x16x32_bf16 v[20:23], v[160:163], v[216:219], v[20:23]
	v_mfma_f32_16x16x32_bf16 v[16:19], v[152:155], v[224:227], v[16:19]
	v_mfma_f32_16x16x32_bf16 v[12:15], v[160:163], v[224:227], v[12:15]
	v_mfma_f32_16x16x32_bf16 v[8:11], v[152:155], v[232:235], v[8:11]
	v_mfma_f32_16x16x32_bf16 v[4:7], v[160:163], v[232:235], v[4:7]
	s_setprio 0
	s_setprio 1
	v_mfma_f32_16x16x32_bf16 v[96:99], v[164:167], v[194:197], v[96:99]
	v_mfma_f32_16x16x32_bf16 v[92:95], v[186:189], v[194:197], v[92:95]
	v_mfma_f32_16x16x32_bf16 v[88:91], v[164:167], v[212:215], v[88:91]
	v_mfma_f32_16x16x32_bf16 v[84:87], v[186:189], v[212:215], v[84:87]
	v_mfma_f32_16x16x32_bf16 v[80:83], v[164:167], v[220:223], v[80:83]
	v_mfma_f32_16x16x32_bf16 v[76:79], v[186:189], v[220:223], v[76:79]
	v_mfma_f32_16x16x32_bf16 v[40:43], v[164:167], v[228:231], v[40:43]
	v_mfma_f32_16x16x32_bf16 v[36:39], v[186:189], v[228:231], v[36:39]
	v_mfma_f32_16x16x32_bf16 v[96:99], v[182:185], v[198:201], v[96:99]
	v_mfma_f32_16x16x32_bf16 v[92:95], v[190:193], v[198:201], v[92:95]
	v_mfma_f32_16x16x32_bf16 v[88:91], v[182:185], v[216:219], v[88:91]
	v_mfma_f32_16x16x32_bf16 v[84:87], v[190:193], v[216:219], v[84:87]
	v_mfma_f32_16x16x32_bf16 v[80:83], v[182:185], v[224:227], v[80:83]
	v_mfma_f32_16x16x32_bf16 v[76:79], v[190:193], v[224:227], v[76:79]
	v_mfma_f32_16x16x32_bf16 v[40:43], v[182:185], v[232:235], v[40:43]
	v_mfma_f32_16x16x32_bf16 v[36:39], v[190:193], v[232:235], v[36:39]
	s_setprio 0
	s_barrier
; #define PG8_STAGE(bufoff, gbase, voff) do { _Pragma("unroll") for (int _i = 0; _i < 2; ++_i) \
;         __builtin_amdgcn_global_load_lds((const unsigned*)((const char*)(gbase) + (voff)[_i]), (PG8_LAS unsigned*)(lds + (bufoff) + ldsw + _i * 8192), 16, 0, 0); } while (0)
; #define PG8_LDA(dst, b, h) do { _Pragma("unroll") for (int m = 0; m < 4; ++m) _Pragma("unroll") for (int k = 0; k < 2; ++k) dst[m][k] = *(const PG8_LAS bf16x8*)(lds + PG8_SA(b, h) + aoff + m * 2048 + k * 1024); } while (0)
; #define PG8_LDB(dst, b, h) do { _Pragma("unroll") for (int n = 0; n < 2; ++n) _Pragma("unroll") for (int k = 0; k < 2; ++k) dst[n][k] = *(const PG8_LAS bf16x8*)(lds + PG8_SB(b, h) + boff + n * 2048 + k * 1024); } while (0)
; #define PG8_MMA(ai, bj, At, Bt) do { __builtin_amdgcn_s_setprio(1); _Pragma("unroll") for (int m = 0; m < 4; ++m) _Pragma("unroll") for (int n = 0; n < 2; ++n) _Pragma("unroll") for (int k = 0; k < 2; ++k) \
;         acc[ai][bj][m][n] = __builtin_amdgcn_mfma_f32_16x16x32_bf16(Bt[n][k], At[m][k], acc[ai][bj][m][n], 0, 0, 0); __builtin_amdgcn_s_setprio(0); } while (0)
; #define PG8_BAR __builtin_amdgcn_s_barrier()
; template <class Epi, class Sched, bool ALIGN_EPI = false, bool SP2 = false>
; __device__ __forceinline__ void gemm_phase(PG8_LAS unsigned char* lds, const Gemm g, const Sched& S, const Epi& E, int wave_s) {
;     ...
;             PG8_LDB(B0, 0, 0); PG8_LDB(B1, 0, 1); PG8_SCHED; PG8_LDA(At, 0, 0); PG8_STAGE(PG8_SA(1, 1), a1 + hstepA, voffA);
;             PG8_WAIT_V(8); PG8_WAIT_L(0); PG8_BAR; PG8_MMA(0, 0, At, B0); PG8_MMA(0, 1, At, B1); PG8_BAR; PG8_SCHED;
;             PG8_LDA(At, 0, 1); PG8_STAGE(PG8_SB(0, 0), b2, voffB); PG8_STAGE(PG8_SB(0, 1), b2 + hstepB, voffB); PG8_STAGE(PG8_SA(0, 0), a2, voffA);
;             PG8_WAIT_V(8); PG8_WAIT_L(0); PG8_BAR; PG8_MMA(1, 0, At, B0); PG8_MMA(1, 1, At, B1); PG8_BAR; PG8_SCHED;
;             PG8_LDB(B0, 1, 0); PG8_LDB(B1, 1, 1); PG8_SCHED; PG8_LDA(At, 1, 0); PG8_STAGE(PG8_SA(0, 1), a2 + hstepA, voffA);
;             PG8_WAIT_V(8); PG8_WAIT_L(0); PG8_BAR; PG8_MMA(0, 0, At, B0); PG8_MMA(0, 1, At, B1); PG8_BAR; PG8_SCHED;
;             PG8_LDA(At, 1, 1); PG8_STAGE(PG8_SB(1, 0), b3, voffB); PG8_STAGE(PG8_SB(1, 1), b3 + hstepB, voffB); PG8_STAGE(PG8_SA(1, 0), a3, voffA);
;             PG8_WAIT_V(8); PG8_WAIT_L(0); PG8_BAR; PG8_MMA(1, 0, At, B0); PG8_MMA(1, 1, At, B1); PG8_BAR; PG8_SCHED;
	s_add_i32 s56, 0, 0x18000
	s_add_i32 s57, 0, 0x1c000
	v_add_u32_e32 v160, s56, v149
	v_add_u32_e32 v173, s57, v149
	ds_read_b128 v[142:145], v160
	ds_read_b128 v[152:155], v160 offset:1024
	ds_read_b128 v[156:159], v160 offset:2048
	ds_read_b128 v[160:163], v160 offset:3072
	ds_read_b128 v[164:167], v173
	ds_read_b128 v[182:185], v173 offset:1024
	ds_read_b128 v[186:189], v173 offset:2048
	ds_read_b128 v[190:193], v173 offset:3072
	s_add_u32 s100, s36, s60
	s_addc_u32 s101, s37, s61
	s_add_u32 s36, s36, 0x80000
	s_addc_u32 s37, s37, 0
	s_mov_b32 m0, s47
	ds_read_b128 v[194:197], v151 offset:32768
	ds_read_b128 v[198:201], v151 offset:33792
	ds_read_b128 v[212:215], v151 offset:34816
	ds_read_b128 v[216:219], v151 offset:35840
	ds_read_b128 v[220:223], v151 offset:36864
	ds_read_b128 v[224:227], v151 offset:37888
	ds_read_b128 v[228:231], v151 offset:38912
	ds_read_b128 v[232:235], v151 offset:39936
	global_load_lds_dwordx4 v134, s[36:37]
	s_mov_b32 m0, s48
	s_nop 0
	global_load_lds_dwordx4 v132, s[36:37]
	s_waitcnt vmcnt(8)
	s_waitcnt lgkmcnt(0)
	s_barrier
	s_setprio 1
	s_waitcnt lgkmcnt(0)
	v_mfma_f32_16x16x32_bf16 v[72:75], v[142:145], v[194:197], v[72:75]
	v_mfma_f32_16x16x32_bf16 v[68:71], v[156:159], v[194:197], v[68:71]
	v_mfma_f32_16x16x32_bf16 v[64:67], v[142:145], v[212:215], v[64:67]
	v_mfma_f32_16x16x32_bf16 v[60:63], v[156:159], v[212:215], v[60:63]
	v_mfma_f32_16x16x32_bf16 v[56:59], v[142:145], v[220:223], v[56:59]
	v_mfma_f32_16x16x32_bf16 v[52:55], v[156:159], v[220:223], v[52:55]
	v_mfma_f32_16x16x32_bf16 v[48:51], v[142:145], v[228:231], v[48:51]
	v_mfma_f32_16x16x32_bf16 v[44:47], v[156:159], v[228:231], v[44:47]
	v_mfma_f32_16x16x32_bf16 v[72:75], v[152:155], v[198:201], v[72:75]
	v_mfma_f32_16x16x32_bf16 v[68:71], v[160:163], v[198:201], v[68:71]
	v_mfma_f32_16x16x32_bf16 v[64:67], v[152:155], v[216:219], v[64:67]
	v_mfma_f32_16x16x32_bf16 v[60:63], v[160:163], v[216:219], v[60:63]
	v_mfma_f32_16x16x32_bf16 v[56:59], v[152:155], v[224:227], v[56:59]
	v_mfma_f32_16x16x32_bf16 v[52:55], v[160:163], v[224:227], v[52:55]
	v_mfma_f32_16x16x32_bf16 v[48:51], v[152:155], v[232:235], v[48:51]
	v_mfma_f32_16x16x32_bf16 v[44:47], v[160:163], v[232:235], v[44:47]
	s_setprio 0
	s_setprio 1
	v_mfma_f32_16x16x32_bf16 v[128:131], v[164:167], v[194:197], v[128:131]
	v_mfma_f32_16x16x32_bf16 v[124:127], v[186:189], v[194:197], v[124:127]
	v_mfma_f32_16x16x32_bf16 v[120:123], v[164:167], v[212:215], v[120:123]
	v_mfma_f32_16x16x32_bf16 v[116:119], v[186:189], v[212:215], v[116:119]
	v_mfma_f32_16x16x32_bf16 v[112:115], v[164:167], v[220:223], v[112:115]
	v_mfma_f32_16x16x32_bf16 v[108:111], v[186:189], v[220:223], v[108:111]
	v_mfma_f32_16x16x32_bf16 v[104:107], v[164:167], v[228:231], v[104:107]
	v_mfma_f32_16x16x32_bf16 v[100:103], v[186:189], v[228:231], v[100:103]
	v_mfma_f32_16x16x32_bf16 v[128:131], v[182:185], v[198:201], v[128:131]
	v_mfma_f32_16x16x32_bf16 v[124:127], v[190:193], v[198:201], v[124:127]
	v_mfma_f32_16x16x32_bf16 v[120:123], v[182:185], v[216:219], v[120:123]
	v_mfma_f32_16x16x32_bf16 v[116:119], v[190:193], v[216:219], v[116:119]
	v_mfma_f32_16x16x32_bf16 v[112:115], v[182:185], v[224:227], v[112:115]
	v_mfma_f32_16x16x32_bf16 v[108:111], v[190:193], v[224:227], v[108:111]
	v_mfma_f32_16x16x32_bf16 v[104:107], v[182:185], v[232:235], v[104:107]
	v_mfma_f32_16x16x32_bf16 v[100:103], v[190:193], v[232:235], v[100:103]
	s_setprio 0
	s_barrier
	s_add_i32 s36, s56, s44
	s_mov_b32 m0, s36
	ds_read_b128 v[194:197], v151 offset:49152
	ds_read_b128 v[198:201], v151 offset:50176
	ds_read_b128 v[212:215], v151 offset:51200
	ds_read_b128 v[216:219], v151 offset:52224
	ds_read_b128 v[220:223], v151 offset:53248
	ds_read_b128 v[224:227], v151 offset:54272
	ds_read_b128 v[228:231], v151 offset:55296
	ds_read_b128 v[232:235], v151 offset:56320
	global_load_lds_dwordx4 v2, s[98:99]
	s_add_i32 m0, s36, 0x2000
	s_add_u32 s26, s26, 0x80080
	s_addc_u32 s27, s27, 0
	s_add_i32 s36, s57, s44
	global_load_lds_dwordx4 v0, s[98:99]
	s_mov_b32 m0, s36
	s_nop 0
	global_load_lds_dwordx4 v2, s[26:27]
	s_add_i32 m0, s36, 0x2000
	s_nop 0
	global_load_lds_dwordx4 v0, s[26:27]
	s_mov_b32 m0, s49
	s_nop 0
	global_load_lds_dwordx4 v134, s[100:101]
	s_mov_b32 m0, s50
	s_nop 0
	global_load_lds_dwordx4 v132, s[100:101]
	s_waitcnt vmcnt(8)
	s_waitcnt lgkmcnt(0)
	s_barrier
	s_setprio 1
	s_waitcnt lgkmcnt(0)
	v_mfma_f32_16x16x32_bf16 v[32:35], v[142:145], v[194:197], v[32:35]
	v_mfma_f32_16x16x32_bf16 v[28:31], v[156:159], v[194:197], v[28:31]
	v_mfma_f32_16x16x32_bf16 v[24:27], v[142:145], v[212:215], v[24:27]
	v_mfma_f32_16x16x32_bf16 v[20:23], v[156:159], v[212:215], v[20:23]
	v_mfma_f32_16x16x32_bf16 v[16:19], v[142:145], v[220:223], v[16:19]
	v_mfma_f32_16x16x32_bf16 v[12:15], v[156:159], v[220:223], v[12:15]
	v_mfma_f32_16x16x32_bf16 v[8:11], v[142:145], v[228:231], v[8:11]
	v_mfma_f32_16x16x32_bf16 v[4:7], v[156:159], v[228:231], v[4:7]
	v_mfma_f32_16x16x32_bf16 v[32:35], v[152:155], v[198:201], v[32:35]
	v_mfma_f32_16x16x32_bf16 v[28:31], v[160:163], v[198:201], v[28:31]
	v_mfma_f32_16x16x32_bf16 v[24:27], v[152:155], v[216:219], v[24:27]
	v_mfma_f32_16x16x32_bf16 v[20:23], v[160:163], v[216:219], v[20:23]
	v_mfma_f32_16x16x32_bf16 v[16:19], v[152:155], v[224:227], v[16:19]
	v_mfma_f32_16x16x32_bf16 v[12:15], v[160:163], v[224:227], v[12:15]
	v_mfma_f32_16x16x32_bf16 v[8:11], v[152:155], v[232:235], v[8:11]
	v_mfma_f32_16x16x32_bf16 v[4:7], v[160:163], v[232:235], v[4:7]
	s_setprio 0
	s_setprio 1
	v_mfma_f32_16x16x32_bf16 v[96:99], v[164:167], v[194:197], v[96:99]
	v_mfma_f32_16x16x32_bf16 v[92:95], v[186:189], v[194:197], v[92:95]
	v_mfma_f32_16x16x32_bf16 v[88:91], v[164:167], v[212:215], v[88:91]
	v_mfma_f32_16x16x32_bf16 v[84:87], v[186:189], v[212:215], v[84:87]
	v_mfma_f32_16x16x32_bf16 v[80:83], v[164:167], v[220:223], v[80:83]
	v_mfma_f32_16x16x32_bf16 v[76:79], v[186:189], v[220:223], v[76:79]
	v_mfma_f32_16x16x32_bf16 v[40:43], v[164:167], v[228:231], v[40:43]
	v_mfma_f32_16x16x32_bf16 v[36:39], v[186:189], v[228:231], v[36:39]
	v_mfma_f32_16x16x32_bf16 v[96:99], v[182:185], v[198:201], v[96:99]
	v_mfma_f32_16x16x32_bf16 v[92:95], v[190:193], v[198:201], v[92:95]
	v_mfma_f32_16x16x32_bf16 v[88:91], v[182:185], v[216:219], v[88:91]
	v_mfma_f32_16x16x32_bf16 v[84:87], v[190:193], v[216:219], v[84:87]
	v_mfma_f32_16x16x32_bf16 v[80:83], v[182:185], v[224:227], v[80:83]
	v_mfma_f32_16x16x32_bf16 v[76:79], v[190:193], v[224:227], v[76:79]
	v_mfma_f32_16x16x32_bf16 v[40:43], v[182:185], v[232:235], v[40:43]
	v_mfma_f32_16x16x32_bf16 v[36:39], v[190:193], v[232:235], v[36:39]
	s_setprio 0
	s_barrier
	s_add_i32 s55, s55, 2
	s_add_u32 s53, s53, 0x100
	s_addc_u32 s54, s54, 0
	s_add_u32 s18, s18, 0x100
	s_addc_u32 s19, s19, 0
	s_cmp_gt_u32 s55, 29
	s_cbranch_scc0 .LBB0_192
	s_and_b64 vcc, exec, s[6:7]
	s_cbranch_vccnz .LBB0_196
	v_lshl_add_u32 v142, s38, 8, v148
	s_cmpk_lg_i32 s33, 0x4a
	s_mov_b64 s[18:19], -1
	s_cbranch_scc1 .LBB0_197

; #define PG8_STAGE(bufoff, gbase, voff) do { _Pragma("unroll") for (int _i = 0; _i < 2; ++_i) \
;         __builtin_amdgcn_global_load_lds((const unsigned*)((const char*)(gbase) + (voff)[_i]), (PG8_LAS unsigned*)(lds + (bufoff) + ldsw + _i * 8192), 16, 0, 0); } while (0)
; #define PG8_LDA(dst, b, h) do { _Pragma("unroll") for (int m = 0; m < 4; ++m) _Pragma("unroll") for (int k = 0; k < 2; ++k) dst[m][k] = *(const PG8_LAS bf16x8*)(lds + PG8_SA(b, h) + aoff + m * 2048 + k * 1024); } while (0)
; #define PG8_LDB(dst, b, h) do { _Pragma("unroll") for (int n = 0; n < 2; ++n) _Pragma("unroll") for (int k = 0; k < 2; ++k) dst[n][k] = *(const PG8_LAS bf16x8*)(lds + PG8_SB(b, h) + boff + n * 2048 + k * 1024); } while (0)
; template <class Epi, class Sched, bool ALIGN_EPI = false, bool SP2 = false>
; __device__ __forceinline__ void gemm_phase(PG8_LAS unsigned char* lds, const Gemm g, const Sched& S, const Epi& E, int wave_s) {
;     ...
;             const bool last = (t == nt - 2);
;             const char* a1 = cA + (size_t)(t + 1) * kstep;
;             const char* a2 = last ? nA : cA + (size_t)(t + 2) * kstep; const char* b2 = last ? nB : cB + (size_t)(t + 2) * kstep;
;             const char* a3 = a2 + kstep; const char* b3 = b2 + kstep;
;             if (last && has_next) S.a_ready(nxt);
;             if constexpr (SP2) {
;             PG8_LDB(B0, 0, 0); PG8_LDB(B1, 0, 1); PG8_SCHED; PG8_LDA(At, 0, 0); PG8_STAGE(PG8_SA(1, 1), a1 + hstepA, voffA);
;             PG8_WAIT_V(8); PG8_WAIT_L(0); PG8_BAR; PG8_MMA(0, 0, At, B0); PG8_MMA(0, 1, At, B1); PG8_BAR; PG8_SCHED;
;             PG8_LDA(At, 0, 1); PG8_STAGE(PG8_SB(0, 0), b2, voffB); PG8_STAGE(PG8_SB(0, 1), b2 + hstepB, voffB); PG8_STAGE(PG8_SA(0, 0), a2, voffA);
;             PG8_WAIT_V(8); PG8_WAIT_L(0); PG8_BAR; PG8_MMA(1, 0, At, B0); PG8_MMA(1, 1, At, B1); PG8_BAR; PG8_SCHED;
;             PG8_LDB(B0, 1, 0); PG8_LDB(B1, 1, 1); PG8_SCHED; PG8_LDA(At, 1, 0); PG8_STAGE(PG8_SA(0, 1), a2 + hstepA, voffA);
;             PG8_WAIT_V(8); PG8_WAIT_L(0); PG8_BAR; PG8_MMA(0, 0, At, B0); PG8_MMA(0, 1, At, B1); PG8_BAR; PG8_SCHED;
;             PG8_LDA(At, 1, 1); PG8_STAGE(PG8_SB(1, 0), b3, voffB); PG8_STAGE(PG8_SB(1, 1), b3 + hstepB, voffB); PG8_STAGE(PG8_SA(1, 0), a3, voffA);
;             PG8_WAIT_V(8); PG8_WAIT_L(0); PG8_BAR; PG8_MMA(1, 0, At, B0); PG8_MMA(1, 1, At, B1); PG8_BAR; PG8_SCHED;
.LBB0_568:
	s_add_u32 s26, s24, 0x100
	s_addc_u32 s27, s25, 0
	s_add_i32 s74, 0, 0x10000
	s_cmp_eq_u32 s67, 4
	s_cselect_b32 s43, s21, s27
	s_cselect_b32 s42, s20, s26
	s_cselect_b32 s39, s19, s66
	s_cselect_b32 s38, s58, s59
	s_add_i32 s75, 0, 0x14000
	v_add_u32_e32 v144, s74, v186
	v_add_u32_e32 v182, s75, v186
	ds_read_b128 v[132:135], v144
	ds_read_b128 v[136:139], v144 offset:1024
	ds_read_b128 v[140:143], v144 offset:2048
	ds_read_b128 v[144:147], v144 offset:3072
	ds_read_b128 v[148:151], v182
	ds_read_b128 v[160:163], v182 offset:1024
	ds_read_b128 v[164:167], v182 offset:2048
	ds_read_b128 v[182:185], v182 offset:3072
	v_lshl_add_u64 v[232:233], s[24:25], 0, v[158:159]
	s_add_i32 m0, s49, 0xc000
	ds_read_b128 v[190:193], v188
	ds_read_b128 v[194:197], v188 offset:1024
	ds_read_b128 v[198:201], v188 offset:2048
	ds_read_b128 v[212:215], v188 offset:3072
	ds_read_b128 v[216:219], v188 offset:4096
	ds_read_b128 v[220:223], v188 offset:5120
	ds_read_b128 v[224:227], v188 offset:6144
	ds_read_b128 v[228:231], v188 offset:7168
	global_load_lds_dwordx4 v[232:233], off
	v_lshl_add_u64 v[232:233], s[24:25], 0, v[156:157]
	s_add_i32 m0, s49, 0xe000
	s_nop 0
	global_load_lds_dwordx4 v[232:233], off
	s_waitcnt vmcnt(8)
	s_waitcnt lgkmcnt(0)
	s_barrier
	s_setprio 1
	s_waitcnt lgkmcnt(0)
	v_mfma_f32_16x16x32_bf16 v[128:131], v[132:135], v[190:193], v[128:131]
	v_mfma_f32_16x16x32_bf16 v[124:127], v[140:143], v[190:193], v[124:127]
	v_mfma_f32_16x16x32_bf16 v[120:123], v[132:135], v[198:201], v[120:123]
	v_mfma_f32_16x16x32_bf16 v[112:115], v[140:143], v[198:201], v[112:115]
	v_mfma_f32_16x16x32_bf16 v[100:103], v[132:135], v[216:219], v[100:103]
	v_mfma_f32_16x16x32_bf16 v[92:95], v[140:143], v[216:219], v[92:95]
	v_mfma_f32_16x16x32_bf16 v[84:87], v[132:135], v[224:227], v[84:87]
	v_mfma_f32_16x16x32_bf16 v[76:79], v[140:143], v[224:227], v[76:79]
	v_mfma_f32_16x16x32_bf16 v[128:131], v[136:139], v[194:197], v[128:131]
	v_mfma_f32_16x16x32_bf16 v[124:127], v[144:147], v[194:197], v[124:127]
	v_mfma_f32_16x16x32_bf16 v[120:123], v[136:139], v[212:215], v[120:123]
	v_mfma_f32_16x16x32_bf16 v[112:115], v[144:147], v[212:215], v[112:115]
	v_mfma_f32_16x16x32_bf16 v[100:103], v[136:139], v[220:223], v[100:103]
	v_mfma_f32_16x16x32_bf16 v[92:95], v[144:147], v[220:223], v[92:95]
	v_mfma_f32_16x16x32_bf16 v[84:87], v[136:139], v[228:231], v[84:87]
	v_mfma_f32_16x16x32_bf16 v[76:79], v[144:147], v[228:231], v[76:79]
	s_setprio 0
	s_setprio 1
	v_mfma_f32_16x16x32_bf16 v[116:119], v[148:151], v[190:193], v[116:119]
	v_mfma_f32_16x16x32_bf16 v[108:111], v[164:167], v[190:193], v[108:111]
	v_mfma_f32_16x16x32_bf16 v[104:107], v[148:151], v[198:201], v[104:107]
	v_mfma_f32_16x16x32_bf16 v[96:99], v[164:167], v[198:201], v[96:99]
	v_mfma_f32_16x16x32_bf16 v[88:91], v[148:151], v[216:219], v[88:91]
	v_mfma_f32_16x16x32_bf16 v[80:83], v[164:167], v[216:219], v[80:83]
	v_mfma_f32_16x16x32_bf16 v[72:75], v[148:151], v[224:227], v[72:75]
	v_mfma_f32_16x16x32_bf16 v[68:71], v[164:167], v[224:227], v[68:71]
	v_mfma_f32_16x16x32_bf16 v[116:119], v[160:163], v[194:197], v[116:119]
	v_mfma_f32_16x16x32_bf16 v[108:111], v[182:185], v[194:197], v[108:111]
	v_mfma_f32_16x16x32_bf16 v[104:107], v[160:163], v[212:215], v[104:107]
	v_mfma_f32_16x16x32_bf16 v[96:99], v[182:185], v[212:215], v[96:99]
	v_mfma_f32_16x16x32_bf16 v[88:91], v[160:163], v[220:223], v[88:91]
	v_mfma_f32_16x16x32_bf16 v[80:83], v[182:185], v[220:223], v[80:83]
	v_mfma_f32_16x16x32_bf16 v[72:75], v[160:163], v[228:231], v[72:75]
	v_mfma_f32_16x16x32_bf16 v[68:71], v[182:185], v[228:231], v[68:71]
	s_setprio 0
	s_barrier
	s_add_i32 s24, s74, s48
	s_add_u32 s98, s38, s60
	s_addc_u32 s99, s39, s61
	s_mov_b32 m0, s24
	ds_read_b128 v[190:193], v188 offset:16384
	ds_read_b128 v[194:197], v188 offset:17408
	ds_read_b128 v[198:201], v188 offset:18432
	ds_read_b128 v[212:215], v188 offset:19456
	ds_read_b128 v[216:219], v188 offset:20480
	ds_read_b128 v[220:223], v188 offset:21504
	ds_read_b128 v[224:227], v188 offset:22528
	ds_read_b128 v[228:231], v188 offset:23552
	global_load_lds_dwordx4 v2, s[38:39]
	s_add_i32 m0, s24, 0x2000
	s_add_u32 s24, s38, 0x20000
	s_addc_u32 s25, s39, 0
	s_add_i32 s74, s75, s48
	global_load_lds_dwordx4 v0, s[38:39]
	s_mov_b32 m0, s74
	s_add_u32 s100, s42, s60
	s_addc_u32 s101, s43, s61
	s_nop 0
	global_load_lds_dwordx4 v2, s[24:25]
	s_add_i32 m0, s74, 0x2000
	s_nop 0
	global_load_lds_dwordx4 v0, s[24:25]
	s_mov_b32 m0, s49
	s_nop 0
	global_load_lds_dwordx4 v154, s[42:43]
	s_mov_b32 m0, s50
	s_nop 0
	global_load_lds_dwordx4 v152, s[42:43]
	s_waitcnt vmcnt(8)
	s_waitcnt lgkmcnt(0)
	s_barrier
; #define PG8_STAGE(bufoff, gbase, voff) do { _Pragma("unroll") for (int _i = 0; _i < 2; ++_i) \
;         __builtin_amdgcn_global_load_lds((const unsigned*)((const char*)(gbase) + (voff)[_i]), (PG8_LAS unsigned*)(lds + (bufoff) + ldsw + _i * 8192), 16, 0, 0); } while (0)
; #define PG8_LDA(dst, b, h) do { _Pragma("unroll") for (int m = 0; m < 4; ++m) _Pragma("unroll") for (int k = 0; k < 2; ++k) dst[m][k] = *(const PG8_LAS bf16x8*)(lds + PG8_SA(b, h) + aoff + m * 2048 + k * 1024); } while (0)
; #define PG8_LDB(dst, b, h) do { _Pragma("unroll") for (int n = 0; n < 2; ++n) _Pragma("unroll") for (int k = 0; k < 2; ++k) dst[n][k] = *(const PG8_LAS bf16x8*)(lds + PG8_SB(b, h) + boff + n * 2048 + k * 1024); } while (0)
; #define PG8_MMA(ai, bj, At, Bt) do { __builtin_amdgcn_s_setprio(1); _Pragma("unroll") for (int m = 0; m < 4; ++m) _Pragma("unroll") for (int n = 0; n < 2; ++n) _Pragma("unroll") for (int k = 0; k < 2; ++k) \
;         acc[ai][bj][m][n] = __builtin_amdgcn_mfma_f32_16x16x32_bf16(Bt[n][k], At[m][k], acc[ai][bj][m][n], 0, 0, 0); __builtin_amdgcn_s_setprio(0); } while (0)
; #define PG8_BAR __builtin_amdgcn_s_barrier()
; template <class Epi, class Sched, bool ALIGN_EPI = false, bool SP2 = false>
; __device__ __forceinline__ void gemm_phase(PG8_LAS unsigned char* lds, const Gemm g, const Sched& S, const Epi& E, int wave_s) {
;     ...
;             PG8_LDB(B0, 0, 0); PG8_LDB(B1, 0, 1); PG8_SCHED; PG8_LDA(At, 0, 0); PG8_STAGE(PG8_SA(1, 1), a1 + hstepA, voffA);
;             PG8_WAIT_V(8); PG8_WAIT_L(0); PG8_BAR; PG8_MMA(0, 0, At, B0); PG8_MMA(0, 1, At, B1); PG8_BAR; PG8_SCHED;
;             PG8_LDA(At, 0, 1); PG8_STAGE(PG8_SB(0, 0), b2, voffB); PG8_STAGE(PG8_SB(0, 1), b2 + hstepB, voffB); PG8_STAGE(PG8_SA(0, 0), a2, voffA);
;             PG8_WAIT_V(8); PG8_WAIT_L(0); PG8_BAR; PG8_MMA(1, 0, At, B0); PG8_MMA(1, 1, At, B1); PG8_BAR; PG8_SCHED;
;             PG8_LDB(B0, 1, 0); PG8_LDB(B1, 1, 1); PG8_SCHED; PG8_LDA(At, 1, 0); PG8_STAGE(PG8_SA(0, 1), a2 + hstepA, voffA);
;             PG8_WAIT_V(8); PG8_WAIT_L(0); PG8_BAR; PG8_MMA(0, 0, At, B0); PG8_MMA(0, 1, At, B1); PG8_BAR; PG8_SCHED;
;             PG8_LDA(At, 1, 1); PG8_STAGE(PG8_SB(1, 0), b3, voffB); PG8_STAGE(PG8_SB(1, 1), b3 + hstepB, voffB); PG8_STAGE(PG8_SA(1, 0), a3, voffA);
;             PG8_WAIT_V(8); PG8_WAIT_L(0); PG8_BAR; PG8_MMA(1, 0, At, B0); PG8_MMA(1, 1, At, B1); PG8_BAR; PG8_SCHED;
	s_setprio 1
	s_waitcnt lgkmcnt(0)
	v_mfma_f32_16x16x32_bf16 v[64:67], v[132:135], v[190:193], v[64:67]
	v_mfma_f32_16x16x32_bf16 v[60:63], v[140:143], v[190:193], v[60:63]
	v_mfma_f32_16x16x32_bf16 v[52:55], v[132:135], v[198:201], v[52:55]
	v_mfma_f32_16x16x32_bf16 v[44:47], v[140:143], v[198:201], v[44:47]
	v_mfma_f32_16x16x32_bf16 v[36:39], v[132:135], v[216:219], v[36:39]
	v_mfma_f32_16x16x32_bf16 v[28:31], v[140:143], v[216:219], v[28:31]
	v_mfma_f32_16x16x32_bf16 v[20:23], v[132:135], v[224:227], v[20:23]
	v_mfma_f32_16x16x32_bf16 v[12:15], v[140:143], v[224:227], v[12:15]
	v_mfma_f32_16x16x32_bf16 v[64:67], v[136:139], v[194:197], v[64:67]
	v_mfma_f32_16x16x32_bf16 v[60:63], v[144:147], v[194:197], v[60:63]
	v_mfma_f32_16x16x32_bf16 v[52:55], v[136:139], v[212:215], v[52:55]
	v_mfma_f32_16x16x32_bf16 v[44:47], v[144:147], v[212:215], v[44:47]
	v_mfma_f32_16x16x32_bf16 v[36:39], v[136:139], v[220:223], v[36:39]
	v_mfma_f32_16x16x32_bf16 v[28:31], v[144:147], v[220:223], v[28:31]
	v_mfma_f32_16x16x32_bf16 v[20:23], v[136:139], v[228:231], v[20:23]
	v_mfma_f32_16x16x32_bf16 v[12:15], v[144:147], v[228:231], v[12:15]
	s_setprio 0
	s_setprio 1
	v_mfma_f32_16x16x32_bf16 v[56:59], v[148:151], v[190:193], v[56:59]
	v_mfma_f32_16x16x32_bf16 v[48:51], v[164:167], v[190:193], v[48:51]
	v_mfma_f32_16x16x32_bf16 v[40:43], v[148:151], v[198:201], v[40:43]
	v_mfma_f32_16x16x32_bf16 v[32:35], v[164:167], v[198:201], v[32:35]
	v_mfma_f32_16x16x32_bf16 v[24:27], v[148:151], v[216:219], v[24:27]
	v_mfma_f32_16x16x32_bf16 v[16:19], v[164:167], v[216:219], v[16:19]
	v_mfma_f32_16x16x32_bf16 v[8:11], v[148:151], v[224:227], v[8:11]
	v_mfma_f32_16x16x32_bf16 v[4:7], v[164:167], v[224:227], v[4:7]
	v_mfma_f32_16x16x32_bf16 v[56:59], v[160:163], v[194:197], v[56:59]
	v_mfma_f32_16x16x32_bf16 v[48:51], v[182:185], v[194:197], v[48:51]
	v_mfma_f32_16x16x32_bf16 v[40:43], v[160:163], v[212:215], v[40:43]
	v_mfma_f32_16x16x32_bf16 v[32:35], v[182:185], v[212:215], v[32:35]
	v_mfma_f32_16x16x32_bf16 v[24:27], v[160:163], v[220:223], v[24:27]
	v_mfma_f32_16x16x32_bf16 v[16:19], v[182:185], v[220:223], v[16:19]
	v_mfma_f32_16x16x32_bf16 v[8:11], v[160:163], v[228:231], v[8:11]
	v_mfma_f32_16x16x32_bf16 v[4:7], v[182:185], v[228:231], v[4:7]
	s_setprio 0
	s_barrier
	s_add_i32 s74, 0, 0x18000
	s_add_i32 s75, 0, 0x1c000
	v_add_u32_e32 v144, s74, v186
	v_add_u32_e32 v182, s75, v186
	ds_read_b128 v[132:135], v144
	ds_read_b128 v[136:139], v144 offset:1024
	ds_read_b128 v[140:143], v144 offset:2048
	ds_read_b128 v[144:147], v144 offset:3072
	ds_read_b128 v[148:151], v182
	ds_read_b128 v[160:163], v182 offset:1024
	ds_read_b128 v[164:167], v182 offset:2048
	ds_read_b128 v[182:185], v182 offset:3072
	s_add_u32 s24, s42, 0x4b0000
	s_addc_u32 s25, s43, 0
	s_mov_b32 m0, s51
	ds_read_b128 v[190:193], v188 offset:32768
	ds_read_b128 v[194:197], v188 offset:33792
	ds_read_b128 v[198:201], v188 offset:34816
	ds_read_b128 v[212:215], v188 offset:35840
	ds_read_b128 v[216:219], v188 offset:36864
	ds_read_b128 v[220:223], v188 offset:37888
	ds_read_b128 v[224:227], v188 offset:38912
	ds_read_b128 v[228:231], v188 offset:39936
	global_load_lds_dwordx4 v154, s[24:25]
	s_mov_b32 m0, s52
	s_nop 0
	global_load_lds_dwordx4 v152, s[24:25]
	s_waitcnt vmcnt(8)
	s_waitcnt lgkmcnt(0)
	s_barrier
	s_setprio 1
	s_waitcnt lgkmcnt(0)
	v_mfma_f32_16x16x32_bf16 v[128:131], v[132:135], v[190:193], v[128:131]
	v_mfma_f32_16x16x32_bf16 v[124:127], v[140:143], v[190:193], v[124:127]
	v_mfma_f32_16x16x32_bf16 v[120:123], v[132:135], v[198:201], v[120:123]
	v_mfma_f32_16x16x32_bf16 v[112:115], v[140:143], v[198:201], v[112:115]
	v_mfma_f32_16x16x32_bf16 v[100:103], v[132:135], v[216:219], v[100:103]
	v_mfma_f32_16x16x32_bf16 v[92:95], v[140:143], v[216:219], v[92:95]
	v_mfma_f32_16x16x32_bf16 v[84:87], v[132:135], v[224:227], v[84:87]
	v_mfma_f32_16x16x32_bf16 v[76:79], v[140:143], v[224:227], v[76:79]
	v_mfma_f32_16x16x32_bf16 v[128:131], v[136:139], v[194:197], v[128:131]
	v_mfma_f32_16x16x32_bf16 v[124:127], v[144:147], v[194:197], v[124:127]
	v_mfma_f32_16x16x32_bf16 v[120:123], v[136:139], v[212:215], v[120:123]
	v_mfma_f32_16x16x32_bf16 v[112:115], v[144:147], v[212:215], v[112:115]
	v_mfma_f32_16x16x32_bf16 v[100:103], v[136:139], v[220:223], v[100:103]
	v_mfma_f32_16x16x32_bf16 v[92:95], v[144:147], v[220:223], v[92:95]
	v_mfma_f32_16x16x32_bf16 v[84:87], v[136:139], v[228:231], v[84:87]
	v_mfma_f32_16x16x32_bf16 v[76:79], v[144:147], v[228:231], v[76:79]
	s_setprio 0
	s_setprio 1
	v_mfma_f32_16x16x32_bf16 v[116:119], v[148:151], v[190:193], v[116:119]
	v_mfma_f32_16x16x32_bf16 v[108:111], v[164:167], v[190:193], v[108:111]
	v_mfma_f32_16x16x32_bf16 v[104:107], v[148:151], v[198:201], v[104:107]
	v_mfma_f32_16x16x32_bf16 v[96:99], v[164:167], v[198:201], v[96:99]
	v_mfma_f32_16x16x32_bf16 v[88:91], v[148:151], v[216:219], v[88:91]
	v_mfma_f32_16x16x32_bf16 v[80:83], v[164:167], v[216:219], v[80:83]
	v_mfma_f32_16x16x32_bf16 v[72:75], v[148:151], v[224:227], v[72:75]
	v_mfma_f32_16x16x32_bf16 v[68:71], v[164:167], v[224:227], v[68:71]
	v_mfma_f32_16x16x32_bf16 v[116:119], v[160:163], v[194:197], v[116:119]
	v_mfma_f32_16x16x32_bf16 v[108:111], v[182:185], v[194:197], v[108:111]
	v_mfma_f32_16x16x32_bf16 v[104:107], v[160:163], v[212:215], v[104:107]
	v_mfma_f32_16x16x32_bf16 v[96:99], v[182:185], v[212:215], v[96:99]
	v_mfma_f32_16x16x32_bf16 v[88:91], v[160:163], v[220:223], v[88:91]
	v_mfma_f32_16x16x32_bf16 v[80:83], v[182:185], v[220:223], v[80:83]
	v_mfma_f32_16x16x32_bf16 v[72:75], v[160:163], v[228:231], v[72:75]
	v_mfma_f32_16x16x32_bf16 v[68:71], v[182:185], v[228:231], v[68:71]
	s_setprio 0
	s_barrier
; #define PG8_STAGE(bufoff, gbase, voff) do { _Pragma("unroll") for (int _i = 0; _i < 2; ++_i) \
;         __builtin_amdgcn_global_load_lds((const unsigned*)((const char*)(gbase) + (voff)[_i]), (PG8_LAS unsigned*)(lds + (bufoff) + ldsw + _i * 8192), 16, 0, 0); } while (0)
; #define PG8_LDA(dst, b, h) do { _Pragma("unroll") for (int m = 0; m < 4; ++m) _Pragma("unroll") for (int k = 0; k < 2; ++k) dst[m][k] = *(const PG8_LAS bf16x8*)(lds + PG8_SA(b, h) + aoff + m * 2048 + k * 1024); } while (0)
; #define PG8_WAIT_V(n) asm volatile("s_waitcnt vmcnt(" #n ")" ::: "memory")
; #define PG8_WAIT_L(n) asm volatile("s_waitcnt lgkmcnt(" #n ")" ::: "memory")
; #define PG8_BAR __builtin_amdgcn_s_barrier()
; template <class Epi, class Sched, bool ALIGN_EPI = false, bool SP2 = false>
; __device__ __forceinline__ void gemm_phase(PG8_LAS unsigned char* lds, const Gemm g, const Sched& S, const Epi& E, int wave_s) {
;     ...
;         for (int t = 0; t < nt; t += 2) {
;             const bool last = (t == nt - 2);
;             const char* a1 = cA + (size_t)(t + 1) * kstep;
;             const char* a2 = last ? nA : cA + (size_t)(t + 2) * kstep; const char* b2 = last ? nB : cB + (size_t)(t + 2) * kstep;
;             const char* a3 = a2 + kstep; const char* b3 = b2 + kstep;
;             if (last && has_next) S.a_ready(nxt);
;             if constexpr (SP2) {
;             PG8_LDB(B0, 0, 0); PG8_LDB(B1, 0, 1); PG8_SCHED; PG8_LDA(At, 0, 0); PG8_STAGE(PG8_SA(1, 1), a1 + hstepA, voffA);
;             PG8_WAIT_V(8); PG8_WAIT_L(0); PG8_BAR; PG8_MMA(0, 0, At, B0); PG8_MMA(0, 1, At, B1); PG8_BAR; PG8_SCHED;
;             PG8_LDA(At, 0, 1); PG8_STAGE(PG8_SB(0, 0), b2, voffB); PG8_STAGE(PG8_SB(0, 1), b2 + hstepB, voffB); PG8_STAGE(PG8_SA(0, 0), a2, voffA);
;             PG8_WAIT_V(8); PG8_WAIT_L(0); PG8_BAR; PG8_MMA(1, 0, At, B0); PG8_MMA(1, 1, At, B1); PG8_BAR; PG8_SCHED;
;             PG8_LDB(B0, 1, 0); PG8_LDB(B1, 1, 1); PG8_SCHED; PG8_LDA(At, 1, 0); PG8_STAGE(PG8_SA(0, 1), a2 + hstepA, voffA);
;             PG8_WAIT_V(8); PG8_WAIT_L(0); PG8_BAR; PG8_MMA(0, 0, At, B0); PG8_MMA(0, 1, At, B1); PG8_BAR; PG8_SCHED;
;             PG8_LDA(At, 1, 1); PG8_STAGE(PG8_SB(1, 0), b3, voffB); PG8_STAGE(PG8_SB(1, 1), b3 + hstepB, voffB); PG8_STAGE(PG8_SA(1, 0), a3, voffA);
;             PG8_WAIT_V(8); PG8_WAIT_L(0); PG8_BAR; PG8_MMA(1, 0, At, B0); PG8_MMA(1, 1, At, B1); PG8_BAR; PG8_SCHED;
	s_add_i32 s24, s74, s48
	s_mov_b32 m0, s24
	ds_read_b128 v[190:193], v188 offset:49152
	ds_read_b128 v[194:197], v188 offset:50176
	ds_read_b128 v[198:201], v188 offset:51200
	ds_read_b128 v[212:215], v188 offset:52224
	ds_read_b128 v[216:219], v188 offset:53248
	ds_read_b128 v[220:223], v188 offset:54272
	ds_read_b128 v[224:227], v188 offset:55296
	ds_read_b128 v[228:231], v188 offset:56320
	global_load_lds_dwordx4 v2, s[98:99]
	s_add_i32 m0, s24, 0x2000
	s_add_u32 s24, s38, 0x20080
	s_addc_u32 s25, s39, 0
	s_add_i32 s38, s75, s48
	global_load_lds_dwordx4 v0, s[98:99]
	s_mov_b32 m0, s38
	s_nop 0
	global_load_lds_dwordx4 v2, s[24:25]
	s_add_i32 m0, s38, 0x2000
	s_nop 0
	global_load_lds_dwordx4 v0, s[24:25]
	s_mov_b32 m0, s53
	s_nop 0
	global_load_lds_dwordx4 v154, s[100:101]
	s_mov_b32 m0, s54
	s_nop 0
	global_load_lds_dwordx4 v152, s[100:101]
	s_waitcnt vmcnt(8)
	s_waitcnt lgkmcnt(0)
	s_barrier
	s_setprio 1
	s_waitcnt lgkmcnt(0)
	v_mfma_f32_16x16x32_bf16 v[64:67], v[132:135], v[190:193], v[64:67]
	v_mfma_f32_16x16x32_bf16 v[60:63], v[140:143], v[190:193], v[60:63]
	v_mfma_f32_16x16x32_bf16 v[52:55], v[132:135], v[198:201], v[52:55]
	v_mfma_f32_16x16x32_bf16 v[44:47], v[140:143], v[198:201], v[44:47]
	v_mfma_f32_16x16x32_bf16 v[36:39], v[132:135], v[216:219], v[36:39]
	v_mfma_f32_16x16x32_bf16 v[28:31], v[140:143], v[216:219], v[28:31]
	v_mfma_f32_16x16x32_bf16 v[20:23], v[132:135], v[224:227], v[20:23]
	v_mfma_f32_16x16x32_bf16 v[12:15], v[140:143], v[224:227], v[12:15]
	v_mfma_f32_16x16x32_bf16 v[64:67], v[136:139], v[194:197], v[64:67]
	v_mfma_f32_16x16x32_bf16 v[60:63], v[144:147], v[194:197], v[60:63]
	v_mfma_f32_16x16x32_bf16 v[52:55], v[136:139], v[212:215], v[52:55]
	v_mfma_f32_16x16x32_bf16 v[44:47], v[144:147], v[212:215], v[44:47]
	v_mfma_f32_16x16x32_bf16 v[36:39], v[136:139], v[220:223], v[36:39]
	v_mfma_f32_16x16x32_bf16 v[28:31], v[144:147], v[220:223], v[28:31]
	v_mfma_f32_16x16x32_bf16 v[20:23], v[136:139], v[228:231], v[20:23]
	v_mfma_f32_16x16x32_bf16 v[12:15], v[144:147], v[228:231], v[12:15]
	s_setprio 0
	s_setprio 1
	v_mfma_f32_16x16x32_bf16 v[56:59], v[148:151], v[190:193], v[56:59]
	v_mfma_f32_16x16x32_bf16 v[48:51], v[164:167], v[190:193], v[48:51]
	v_mfma_f32_16x16x32_bf16 v[40:43], v[148:151], v[198:201], v[40:43]
	v_mfma_f32_16x16x32_bf16 v[32:35], v[164:167], v[198:201], v[32:35]
	v_mfma_f32_16x16x32_bf16 v[24:27], v[148:151], v[216:219], v[24:27]
	v_mfma_f32_16x16x32_bf16 v[16:19], v[164:167], v[216:219], v[16:19]
	v_mfma_f32_16x16x32_bf16 v[8:11], v[148:151], v[224:227], v[8:11]
	v_mfma_f32_16x16x32_bf16 v[4:7], v[164:167], v[224:227], v[4:7]
	v_mfma_f32_16x16x32_bf16 v[56:59], v[160:163], v[194:197], v[56:59]
	v_mfma_f32_16x16x32_bf16 v[48:51], v[182:185], v[194:197], v[48:51]
	v_mfma_f32_16x16x32_bf16 v[40:43], v[160:163], v[212:215], v[40:43]
	v_mfma_f32_16x16x32_bf16 v[32:35], v[182:185], v[212:215], v[32:35]
	v_mfma_f32_16x16x32_bf16 v[24:27], v[160:163], v[220:223], v[24:27]
	v_mfma_f32_16x16x32_bf16 v[16:19], v[182:185], v[220:223], v[16:19]
	v_mfma_f32_16x16x32_bf16 v[8:11], v[160:163], v[228:231], v[8:11]
	v_mfma_f32_16x16x32_bf16 v[4:7], v[182:185], v[228:231], v[4:7]
	s_setprio 0
	s_barrier
	s_add_i32 s67, s67, 2
	s_add_u32 s59, s59, 0x100
	s_addc_u32 s66, s66, 0
	s_cmp_gt_u32 s67, 5
	s_mov_b64 s[24:25], s[26:27]
	s_cbranch_scc0 .LBB0_568
	s_and_b64 vcc, exec, s[16:17]
	s_cbranch_vccz .LBB0_571
	s_barrier

; #define PG8_STAGE(bufoff, gbase, voff) do { _Pragma("unroll") for (int _i = 0; _i < 2; ++_i) \
;         __builtin_amdgcn_global_load_lds((const unsigned*)((const char*)(gbase) + (voff)[_i]), (PG8_LAS unsigned*)(lds + (bufoff) + ldsw + _i * 8192), 16, 0, 0); } while (0)
; #define PG8_LDA(dst, b, h) do { _Pragma("unroll") for (int m = 0; m < 4; ++m) _Pragma("unroll") for (int k = 0; k < 2; ++k) dst[m][k] = *(const PG8_LAS bf16x8*)(lds + PG8_SA(b, h) + aoff + m * 2048 + k * 1024); } while (0)
; #define PG8_LDB(dst, b, h) do { _Pragma("unroll") for (int n = 0; n < 2; ++n) _Pragma("unroll") for (int k = 0; k < 2; ++k) dst[n][k] = *(const PG8_LAS bf16x8*)(lds + PG8_SB(b, h) + boff + n * 2048 + k * 1024); } while (0)
; template <class Epi, class Sched, bool ALIGN_EPI = false, bool SP2 = false>
; __device__ __forceinline__ void gemm_phase(PG8_LAS unsigned char* lds, const Gemm g, const Sched& S, const Epi& E, int wave_s) {
;     ...
;             const bool last = (t == nt - 2);
;             const char* a1 = cA + (size_t)(t + 1) * kstep;
;             const char* a2 = last ? nA : cA + (size_t)(t + 2) * kstep; const char* b2 = last ? nB : cB + (size_t)(t + 2) * kstep;
;             const char* a3 = a2 + kstep; const char* b3 = b2 + kstep;
;             if (last && has_next) S.a_ready(nxt);
;             if constexpr (SP2) {
;             PG8_LDB(B0, 0, 0); PG8_LDB(B1, 0, 1); PG8_SCHED; PG8_LDA(At, 0, 0); PG8_STAGE(PG8_SA(1, 1), a1 + hstepA, voffA);
;             PG8_WAIT_V(8); PG8_WAIT_L(0); PG8_BAR; PG8_MMA(0, 0, At, B0); PG8_MMA(0, 1, At, B1); PG8_BAR; PG8_SCHED;
;             PG8_LDA(At, 0, 1); PG8_STAGE(PG8_SB(0, 0), b2, voffB); PG8_STAGE(PG8_SB(0, 1), b2 + hstepB, voffB); PG8_STAGE(PG8_SA(0, 0), a2, voffA);
;             PG8_WAIT_V(8); PG8_WAIT_L(0); PG8_BAR; PG8_MMA(1, 0, At, B0); PG8_MMA(1, 1, At, B1); PG8_BAR; PG8_SCHED;
;             PG8_LDB(B0, 1, 0); PG8_LDB(B1, 1, 1); PG8_SCHED; PG8_LDA(At, 1, 0); PG8_STAGE(PG8_SA(0, 1), a2 + hstepA, voffA);
;             PG8_WAIT_V(8); PG8_WAIT_L(0); PG8_BAR; PG8_MMA(0, 0, At, B0); PG8_MMA(0, 1, At, B1); PG8_BAR; PG8_SCHED;
;             PG8_LDA(At, 1, 1); PG8_STAGE(PG8_SB(1, 0), b3, voffB); PG8_STAGE(PG8_SB(1, 1), b3 + hstepB, voffB); PG8_STAGE(PG8_SA(1, 0), a3, voffA);
;             PG8_WAIT_V(8); PG8_WAIT_L(0); PG8_BAR; PG8_MMA(1, 0, At, B0); PG8_MMA(1, 1, At, B1); PG8_BAR; PG8_SCHED;
.LBB0_590:
	s_add_u32 s0, s4, 0x100
	s_addc_u32 s1, s5, 0
	s_add_i32 s58, 0, 0x10000
	s_cmp_eq_u32 s57, 60
	s_cselect_b32 s17, s49, s1
	s_cselect_b32 s16, s48, s0
	s_cselect_b32 s7, s38, s56
	s_cselect_b32 s6, s39, s47
	s_add_i32 s59, 0, 0x14000
	v_add_u32_e32 v144, s58, v194
	v_add_u32_e32 v182, s59, v194
	ds_read_b128 v[100:103], v144
	ds_read_b128 v[120:123], v144 offset:1024
	ds_read_b128 v[124:127], v144 offset:2048
	ds_read_b128 v[144:147], v144 offset:3072
	ds_read_b128 v[148:151], v182
	ds_read_b128 v[152:155], v182 offset:1024
	ds_read_b128 v[156:159], v182 offset:2048
	ds_read_b128 v[182:185], v182 offset:3072
	v_lshl_add_u64 v[232:233], s[4:5], 0, v[166:167]
	s_add_i32 m0, s25, 0xc000
	ds_read_b128 v[186:189], v196
	ds_read_b128 v[190:193], v196 offset:1024
	ds_read_b128 v[198:201], v196 offset:2048
	ds_read_b128 v[212:215], v196 offset:3072
	ds_read_b128 v[216:219], v196 offset:4096
	ds_read_b128 v[220:223], v196 offset:5120
	ds_read_b128 v[224:227], v196 offset:6144
	ds_read_b128 v[228:231], v196 offset:7168
	global_load_lds_dwordx4 v[232:233], off
	v_lshl_add_u64 v[232:233], s[4:5], 0, v[164:165]
	s_add_i32 m0, s25, 0xe000
	s_nop 0
	global_load_lds_dwordx4 v[232:233], off
	s_waitcnt vmcnt(8)
	s_waitcnt lgkmcnt(0)
	s_barrier
	s_setprio 1
	s_waitcnt lgkmcnt(0)
	v_mfma_f32_16x16x32_bf16 v[140:143], v[100:103], v[186:189], v[140:143]
	v_mfma_f32_16x16x32_bf16 v[136:139], v[124:127], v[186:189], v[136:139]
	v_mfma_f32_16x16x32_bf16 v[116:119], v[100:103], v[198:201], v[116:119]
	v_mfma_f32_16x16x32_bf16 v[112:115], v[124:127], v[198:201], v[112:115]
	v_mfma_f32_16x16x32_bf16 v[96:99], v[100:103], v[216:219], v[96:99]
	v_mfma_f32_16x16x32_bf16 v[92:95], v[124:127], v[216:219], v[92:95]
	v_mfma_f32_16x16x32_bf16 v[80:83], v[100:103], v[224:227], v[80:83]
	v_mfma_f32_16x16x32_bf16 v[76:79], v[124:127], v[224:227], v[76:79]
	v_mfma_f32_16x16x32_bf16 v[140:143], v[120:123], v[190:193], v[140:143]
	v_mfma_f32_16x16x32_bf16 v[136:139], v[144:147], v[190:193], v[136:139]
	v_mfma_f32_16x16x32_bf16 v[116:119], v[120:123], v[212:215], v[116:119]
	v_mfma_f32_16x16x32_bf16 v[112:115], v[144:147], v[212:215], v[112:115]
	v_mfma_f32_16x16x32_bf16 v[96:99], v[120:123], v[220:223], v[96:99]
	v_mfma_f32_16x16x32_bf16 v[92:95], v[144:147], v[220:223], v[92:95]
	v_mfma_f32_16x16x32_bf16 v[80:83], v[120:123], v[228:231], v[80:83]
	v_mfma_f32_16x16x32_bf16 v[76:79], v[144:147], v[228:231], v[76:79]
	s_setprio 0
	s_setprio 1
	v_mfma_f32_16x16x32_bf16 v[132:135], v[148:151], v[186:189], v[132:135]
	v_mfma_f32_16x16x32_bf16 v[128:131], v[156:159], v[186:189], v[128:131]
	v_mfma_f32_16x16x32_bf16 v[108:111], v[148:151], v[198:201], v[108:111]
	v_mfma_f32_16x16x32_bf16 v[104:107], v[156:159], v[198:201], v[104:107]
	v_mfma_f32_16x16x32_bf16 v[88:91], v[148:151], v[216:219], v[88:91]
	v_mfma_f32_16x16x32_bf16 v[84:87], v[156:159], v[216:219], v[84:87]
	v_mfma_f32_16x16x32_bf16 v[72:75], v[148:151], v[224:227], v[72:75]
	v_mfma_f32_16x16x32_bf16 v[68:71], v[156:159], v[224:227], v[68:71]
	v_mfma_f32_16x16x32_bf16 v[132:135], v[152:155], v[190:193], v[132:135]
	v_mfma_f32_16x16x32_bf16 v[128:131], v[182:185], v[190:193], v[128:131]
	v_mfma_f32_16x16x32_bf16 v[108:111], v[152:155], v[212:215], v[108:111]
	v_mfma_f32_16x16x32_bf16 v[104:107], v[182:185], v[212:215], v[104:107]
	v_mfma_f32_16x16x32_bf16 v[88:91], v[152:155], v[220:223], v[88:91]
	v_mfma_f32_16x16x32_bf16 v[84:87], v[182:185], v[220:223], v[84:87]
	v_mfma_f32_16x16x32_bf16 v[72:75], v[152:155], v[228:231], v[72:75]
	v_mfma_f32_16x16x32_bf16 v[68:71], v[182:185], v[228:231], v[68:71]
	s_setprio 0
	s_barrier
	s_add_i32 s4, s58, s24
	s_add_u32 s98, s6, s60
	s_addc_u32 s99, s7, s61
	s_mov_b32 m0, s4
	ds_read_b128 v[186:189], v196 offset:16384
	ds_read_b128 v[190:193], v196 offset:17408
	ds_read_b128 v[198:201], v196 offset:18432
	ds_read_b128 v[212:215], v196 offset:19456
	ds_read_b128 v[216:219], v196 offset:20480
	ds_read_b128 v[220:223], v196 offset:21504
	ds_read_b128 v[224:227], v196 offset:22528
	ds_read_b128 v[228:231], v196 offset:23552
	global_load_lds_dwordx4 v2, s[6:7]
	s_add_i32 m0, s4, 0x2000
	s_add_u32 s4, s6, 0x100000
	s_addc_u32 s5, s7, 0
	s_add_i32 s58, s59, s24
	global_load_lds_dwordx4 v0, s[6:7]
	s_mov_b32 m0, s58
	s_add_u32 s100, s16, s60
	s_addc_u32 s101, s17, s61
	s_nop 0
	global_load_lds_dwordx4 v2, s[4:5]
	s_add_i32 m0, s58, 0x2000
	s_nop 0
	global_load_lds_dwordx4 v0, s[4:5]
	s_mov_b32 m0, s25
	s_nop 0
	global_load_lds_dwordx4 v162, s[16:17]
	s_mov_b32 m0, s26
	s_nop 0
	global_load_lds_dwordx4 v160, s[16:17]
	s_waitcnt vmcnt(8)
	s_waitcnt lgkmcnt(0)
	s_barrier
; #define PG8_STAGE(bufoff, gbase, voff) do { _Pragma("unroll") for (int _i = 0; _i < 2; ++_i) \
;         __builtin_amdgcn_global_load_lds((const unsigned*)((const char*)(gbase) + (voff)[_i]), (PG8_LAS unsigned*)(lds + (bufoff) + ldsw + _i * 8192), 16, 0, 0); } while (0)
; #define PG8_LDA(dst, b, h) do { _Pragma("unroll") for (int m = 0; m < 4; ++m) _Pragma("unroll") for (int k = 0; k < 2; ++k) dst[m][k] = *(const PG8_LAS bf16x8*)(lds + PG8_SA(b, h) + aoff + m * 2048 + k * 1024); } while (0)
; #define PG8_LDB(dst, b, h) do { _Pragma("unroll") for (int n = 0; n < 2; ++n) _Pragma("unroll") for (int k = 0; k < 2; ++k) dst[n][k] = *(const PG8_LAS bf16x8*)(lds + PG8_SB(b, h) + boff + n * 2048 + k * 1024); } while (0)
; #define PG8_MMA(ai, bj, At, Bt) do { __builtin_amdgcn_s_setprio(1); _Pragma("unroll") for (int m = 0; m < 4; ++m) _Pragma("unroll") for (int n = 0; n < 2; ++n) _Pragma("unroll") for (int k = 0; k < 2; ++k) \
;         acc[ai][bj][m][n] = __builtin_amdgcn_mfma_f32_16x16x32_bf16(Bt[n][k], At[m][k], acc[ai][bj][m][n], 0, 0, 0); __builtin_amdgcn_s_setprio(0); } while (0)
; #define PG8_BAR __builtin_amdgcn_s_barrier()
; template <class Epi, class Sched, bool ALIGN_EPI = false, bool SP2 = false>
; __device__ __forceinline__ void gemm_phase(PG8_LAS unsigned char* lds, const Gemm g, const Sched& S, const Epi& E, int wave_s) {
;     ...
;             PG8_LDB(B0, 0, 0); PG8_LDB(B1, 0, 1); PG8_SCHED; PG8_LDA(At, 0, 0); PG8_STAGE(PG8_SA(1, 1), a1 + hstepA, voffA);
;             PG8_WAIT_V(8); PG8_WAIT_L(0); PG8_BAR; PG8_MMA(0, 0, At, B0); PG8_MMA(0, 1, At, B1); PG8_BAR; PG8_SCHED;
;             PG8_LDA(At, 0, 1); PG8_STAGE(PG8_SB(0, 0), b2, voffB); PG8_STAGE(PG8_SB(0, 1), b2 + hstepB, voffB); PG8_STAGE(PG8_SA(0, 0), a2, voffA);
;             PG8_WAIT_V(8); PG8_WAIT_L(0); PG8_BAR; PG8_MMA(1, 0, At, B0); PG8_MMA(1, 1, At, B1); PG8_BAR; PG8_SCHED;
;             PG8_LDB(B0, 1, 0); PG8_LDB(B1, 1, 1); PG8_SCHED; PG8_LDA(At, 1, 0); PG8_STAGE(PG8_SA(0, 1), a2 + hstepA, voffA);
;             PG8_WAIT_V(8); PG8_WAIT_L(0); PG8_BAR; PG8_MMA(0, 0, At, B0); PG8_MMA(0, 1, At, B1); PG8_BAR; PG8_SCHED;
;             PG8_LDA(At, 1, 1); PG8_STAGE(PG8_SB(1, 0), b3, voffB); PG8_STAGE(PG8_SB(1, 1), b3 + hstepB, voffB); PG8_STAGE(PG8_SA(1, 0), a3, voffA);
;             PG8_WAIT_V(8); PG8_WAIT_L(0); PG8_BAR; PG8_MMA(1, 0, At, B0); PG8_MMA(1, 1, At, B1); PG8_BAR; PG8_SCHED;
	s_setprio 1
	s_waitcnt lgkmcnt(0)
	v_mfma_f32_16x16x32_bf16 v[64:67], v[100:103], v[186:189], v[64:67]
	v_mfma_f32_16x16x32_bf16 v[60:63], v[124:127], v[186:189], v[60:63]
	v_mfma_f32_16x16x32_bf16 v[48:51], v[100:103], v[198:201], v[48:51]
	v_mfma_f32_16x16x32_bf16 v[44:47], v[124:127], v[198:201], v[44:47]
	v_mfma_f32_16x16x32_bf16 v[32:35], v[100:103], v[216:219], v[32:35]
	v_mfma_f32_16x16x32_bf16 v[28:31], v[124:127], v[216:219], v[28:31]
	v_mfma_f32_16x16x32_bf16 v[16:19], v[100:103], v[224:227], v[16:19]
	v_mfma_f32_16x16x32_bf16 v[12:15], v[124:127], v[224:227], v[12:15]
	v_mfma_f32_16x16x32_bf16 v[64:67], v[120:123], v[190:193], v[64:67]
	v_mfma_f32_16x16x32_bf16 v[60:63], v[144:147], v[190:193], v[60:63]
	v_mfma_f32_16x16x32_bf16 v[48:51], v[120:123], v[212:215], v[48:51]
	v_mfma_f32_16x16x32_bf16 v[44:47], v[144:147], v[212:215], v[44:47]
	v_mfma_f32_16x16x32_bf16 v[32:35], v[120:123], v[220:223], v[32:35]
	v_mfma_f32_16x16x32_bf16 v[28:31], v[144:147], v[220:223], v[28:31]
	v_mfma_f32_16x16x32_bf16 v[16:19], v[120:123], v[228:231], v[16:19]
	v_mfma_f32_16x16x32_bf16 v[12:15], v[144:147], v[228:231], v[12:15]
	s_setprio 0
	s_setprio 1
	v_mfma_f32_16x16x32_bf16 v[56:59], v[148:151], v[186:189], v[56:59]
	v_mfma_f32_16x16x32_bf16 v[52:55], v[156:159], v[186:189], v[52:55]
	v_mfma_f32_16x16x32_bf16 v[40:43], v[148:151], v[198:201], v[40:43]
	v_mfma_f32_16x16x32_bf16 v[36:39], v[156:159], v[198:201], v[36:39]
	v_mfma_f32_16x16x32_bf16 v[24:27], v[148:151], v[216:219], v[24:27]
	v_mfma_f32_16x16x32_bf16 v[20:23], v[156:159], v[216:219], v[20:23]
	v_mfma_f32_16x16x32_bf16 v[8:11], v[148:151], v[224:227], v[8:11]
	v_mfma_f32_16x16x32_bf16 v[4:7], v[156:159], v[224:227], v[4:7]
	v_mfma_f32_16x16x32_bf16 v[56:59], v[152:155], v[190:193], v[56:59]
	v_mfma_f32_16x16x32_bf16 v[52:55], v[182:185], v[190:193], v[52:55]
	v_mfma_f32_16x16x32_bf16 v[40:43], v[152:155], v[212:215], v[40:43]
	v_mfma_f32_16x16x32_bf16 v[36:39], v[182:185], v[212:215], v[36:39]
	v_mfma_f32_16x16x32_bf16 v[24:27], v[152:155], v[220:223], v[24:27]
	v_mfma_f32_16x16x32_bf16 v[20:23], v[182:185], v[220:223], v[20:23]
	v_mfma_f32_16x16x32_bf16 v[8:11], v[152:155], v[228:231], v[8:11]
	v_mfma_f32_16x16x32_bf16 v[4:7], v[182:185], v[228:231], v[4:7]
	s_setprio 0
	s_barrier
	s_add_i32 s58, 0, 0x18000
	s_add_i32 s59, 0, 0x1c000
	v_add_u32_e32 v144, s58, v194
	v_add_u32_e32 v182, s59, v194
	ds_read_b128 v[100:103], v144
	ds_read_b128 v[120:123], v144 offset:1024
	ds_read_b128 v[124:127], v144 offset:2048
	ds_read_b128 v[144:147], v144 offset:3072
	ds_read_b128 v[148:151], v182
	ds_read_b128 v[152:155], v182 offset:1024
	ds_read_b128 v[156:159], v182 offset:2048
	ds_read_b128 v[182:185], v182 offset:3072
	s_add_u32 s4, s16, 0x4b0000
	s_addc_u32 s5, s17, 0
	s_mov_b32 m0, s27
	ds_read_b128 v[186:189], v196 offset:32768
	ds_read_b128 v[190:193], v196 offset:33792
	ds_read_b128 v[198:201], v196 offset:34816
	ds_read_b128 v[212:215], v196 offset:35840
	ds_read_b128 v[216:219], v196 offset:36864
	ds_read_b128 v[220:223], v196 offset:37888
	ds_read_b128 v[224:227], v196 offset:38912
	ds_read_b128 v[228:231], v196 offset:39936
	global_load_lds_dwordx4 v162, s[4:5]
	s_mov_b32 m0, s30
	s_nop 0
	global_load_lds_dwordx4 v160, s[4:5]
	s_waitcnt vmcnt(8)
	s_waitcnt lgkmcnt(0)
	s_barrier
	s_setprio 1
	s_waitcnt lgkmcnt(0)
	v_mfma_f32_16x16x32_bf16 v[140:143], v[100:103], v[186:189], v[140:143]
	v_mfma_f32_16x16x32_bf16 v[136:139], v[124:127], v[186:189], v[136:139]
	v_mfma_f32_16x16x32_bf16 v[116:119], v[100:103], v[198:201], v[116:119]
	v_mfma_f32_16x16x32_bf16 v[112:115], v[124:127], v[198:201], v[112:115]
	v_mfma_f32_16x16x32_bf16 v[96:99], v[100:103], v[216:219], v[96:99]
	v_mfma_f32_16x16x32_bf16 v[92:95], v[124:127], v[216:219], v[92:95]
	v_mfma_f32_16x16x32_bf16 v[80:83], v[100:103], v[224:227], v[80:83]
	v_mfma_f32_16x16x32_bf16 v[76:79], v[124:127], v[224:227], v[76:79]
	v_mfma_f32_16x16x32_bf16 v[140:143], v[120:123], v[190:193], v[140:143]
	v_mfma_f32_16x16x32_bf16 v[136:139], v[144:147], v[190:193], v[136:139]
	v_mfma_f32_16x16x32_bf16 v[116:119], v[120:123], v[212:215], v[116:119]
	v_mfma_f32_16x16x32_bf16 v[112:115], v[144:147], v[212:215], v[112:115]
	v_mfma_f32_16x16x32_bf16 v[96:99], v[120:123], v[220:223], v[96:99]
	v_mfma_f32_16x16x32_bf16 v[92:95], v[144:147], v[220:223], v[92:95]
	v_mfma_f32_16x16x32_bf16 v[80:83], v[120:123], v[228:231], v[80:83]
	v_mfma_f32_16x16x32_bf16 v[76:79], v[144:147], v[228:231], v[76:79]
	s_setprio 0
	s_setprio 1
	v_mfma_f32_16x16x32_bf16 v[132:135], v[148:151], v[186:189], v[132:135]
	v_mfma_f32_16x16x32_bf16 v[128:131], v[156:159], v[186:189], v[128:131]
	v_mfma_f32_16x16x32_bf16 v[108:111], v[148:151], v[198:201], v[108:111]
	v_mfma_f32_16x16x32_bf16 v[104:107], v[156:159], v[198:201], v[104:107]
	v_mfma_f32_16x16x32_bf16 v[88:91], v[148:151], v[216:219], v[88:91]
	v_mfma_f32_16x16x32_bf16 v[84:87], v[156:159], v[216:219], v[84:87]
	v_mfma_f32_16x16x32_bf16 v[72:75], v[148:151], v[224:227], v[72:75]
	v_mfma_f32_16x16x32_bf16 v[68:71], v[156:159], v[224:227], v[68:71]
	v_mfma_f32_16x16x32_bf16 v[132:135], v[152:155], v[190:193], v[132:135]
	v_mfma_f32_16x16x32_bf16 v[128:131], v[182:185], v[190:193], v[128:131]
	v_mfma_f32_16x16x32_bf16 v[108:111], v[152:155], v[212:215], v[108:111]
	v_mfma_f32_16x16x32_bf16 v[104:107], v[182:185], v[212:215], v[104:107]
	v_mfma_f32_16x16x32_bf16 v[88:91], v[152:155], v[220:223], v[88:91]
	v_mfma_f32_16x16x32_bf16 v[84:87], v[182:185], v[220:223], v[84:87]
	v_mfma_f32_16x16x32_bf16 v[72:75], v[152:155], v[228:231], v[72:75]
	v_mfma_f32_16x16x32_bf16 v[68:71], v[182:185], v[228:231], v[68:71]
	s_setprio 0
	s_barrier
; #define PG8_STAGE(bufoff, gbase, voff) do { _Pragma("unroll") for (int _i = 0; _i < 2; ++_i) \
;         __builtin_amdgcn_global_load_lds((const unsigned*)((const char*)(gbase) + (voff)[_i]), (PG8_LAS unsigned*)(lds + (bufoff) + ldsw + _i * 8192), 16, 0, 0); } while (0)
; #define PG8_LDA(dst, b, h) do { _Pragma("unroll") for (int m = 0; m < 4; ++m) _Pragma("unroll") for (int k = 0; k < 2; ++k) dst[m][k] = *(const PG8_LAS bf16x8*)(lds + PG8_SA(b, h) + aoff + m * 2048 + k * 1024); } while (0)
; #define PG8_WAIT_V(n) asm volatile("s_waitcnt vmcnt(" #n ")" ::: "memory")
; #define PG8_WAIT_L(n) asm volatile("s_waitcnt lgkmcnt(" #n ")" ::: "memory")
; #define PG8_BAR __builtin_amdgcn_s_barrier()
; template <class Epi, class Sched, bool ALIGN_EPI = false, bool SP2 = false>
; __device__ __forceinline__ void gemm_phase(PG8_LAS unsigned char* lds, const Gemm g, const Sched& S, const Epi& E, int wave_s) {
;     ...
;         for (int t = 0; t < nt; t += 2) {
;             const bool last = (t == nt - 2);
;             const char* a1 = cA + (size_t)(t + 1) * kstep;
;             const char* a2 = last ? nA : cA + (size_t)(t + 2) * kstep; const char* b2 = last ? nB : cB + (size_t)(t + 2) * kstep;
;             const char* a3 = a2 + kstep; const char* b3 = b2 + kstep;
;             if (last && has_next) S.a_ready(nxt);
;             if constexpr (SP2) {
;             PG8_LDB(B0, 0, 0); PG8_LDB(B1, 0, 1); PG8_SCHED; PG8_LDA(At, 0, 0); PG8_STAGE(PG8_SA(1, 1), a1 + hstepA, voffA);
;             PG8_WAIT_V(8); PG8_WAIT_L(0); PG8_BAR; PG8_MMA(0, 0, At, B0); PG8_MMA(0, 1, At, B1); PG8_BAR; PG8_SCHED;
;             PG8_LDA(At, 0, 1); PG8_STAGE(PG8_SB(0, 0), b2, voffB); PG8_STAGE(PG8_SB(0, 1), b2 + hstepB, voffB); PG8_STAGE(PG8_SA(0, 0), a2, voffA);
;             PG8_WAIT_V(8); PG8_WAIT_L(0); PG8_BAR; PG8_MMA(1, 0, At, B0); PG8_MMA(1, 1, At, B1); PG8_BAR; PG8_SCHED;
;             PG8_LDB(B0, 1, 0); PG8_LDB(B1, 1, 1); PG8_SCHED; PG8_LDA(At, 1, 0); PG8_STAGE(PG8_SA(0, 1), a2 + hstepA, voffA);
;             PG8_WAIT_V(8); PG8_WAIT_L(0); PG8_BAR; PG8_MMA(0, 0, At, B0); PG8_MMA(0, 1, At, B1); PG8_BAR; PG8_SCHED;
;             PG8_LDA(At, 1, 1); PG8_STAGE(PG8_SB(1, 0), b3, voffB); PG8_STAGE(PG8_SB(1, 1), b3 + hstepB, voffB); PG8_STAGE(PG8_SA(1, 0), a3, voffA);
;             PG8_WAIT_V(8); PG8_WAIT_L(0); PG8_BAR; PG8_MMA(1, 0, At, B0); PG8_MMA(1, 1, At, B1); PG8_BAR; PG8_SCHED;
	s_add_i32 s4, s58, s24
	s_mov_b32 m0, s4
	ds_read_b128 v[186:189], v196 offset:49152
	ds_read_b128 v[190:193], v196 offset:50176
	ds_read_b128 v[198:201], v196 offset:51200
	ds_read_b128 v[212:215], v196 offset:52224
	ds_read_b128 v[216:219], v196 offset:53248
	ds_read_b128 v[220:223], v196 offset:54272
	ds_read_b128 v[224:227], v196 offset:55296
	ds_read_b128 v[228:231], v196 offset:56320
	global_load_lds_dwordx4 v2, s[98:99]
	s_add_i32 m0, s4, 0x2000
	s_add_u32 s4, s6, 0x100080
	s_addc_u32 s5, s7, 0
	s_add_i32 s6, s59, s24
	global_load_lds_dwordx4 v0, s[98:99]
	s_mov_b32 m0, s6
	s_nop 0
	global_load_lds_dwordx4 v2, s[4:5]
	s_add_i32 m0, s6, 0x2000
	s_nop 0
	global_load_lds_dwordx4 v0, s[4:5]
	s_mov_b32 m0, s52
	s_nop 0
	global_load_lds_dwordx4 v162, s[100:101]
	s_mov_b32 m0, s53
	s_nop 0
	global_load_lds_dwordx4 v160, s[100:101]
	s_waitcnt vmcnt(8)
	s_waitcnt lgkmcnt(0)
	s_barrier
	s_setprio 1
	s_waitcnt lgkmcnt(0)
	v_mfma_f32_16x16x32_bf16 v[64:67], v[100:103], v[186:189], v[64:67]
	v_mfma_f32_16x16x32_bf16 v[60:63], v[124:127], v[186:189], v[60:63]
	v_mfma_f32_16x16x32_bf16 v[48:51], v[100:103], v[198:201], v[48:51]
	v_mfma_f32_16x16x32_bf16 v[44:47], v[124:127], v[198:201], v[44:47]
	v_mfma_f32_16x16x32_bf16 v[32:35], v[100:103], v[216:219], v[32:35]
	v_mfma_f32_16x16x32_bf16 v[28:31], v[124:127], v[216:219], v[28:31]
	v_mfma_f32_16x16x32_bf16 v[16:19], v[100:103], v[224:227], v[16:19]
	v_mfma_f32_16x16x32_bf16 v[12:15], v[124:127], v[224:227], v[12:15]
	v_mfma_f32_16x16x32_bf16 v[64:67], v[120:123], v[190:193], v[64:67]
	v_mfma_f32_16x16x32_bf16 v[60:63], v[144:147], v[190:193], v[60:63]
	v_mfma_f32_16x16x32_bf16 v[48:51], v[120:123], v[212:215], v[48:51]
	v_mfma_f32_16x16x32_bf16 v[44:47], v[144:147], v[212:215], v[44:47]
	v_mfma_f32_16x16x32_bf16 v[32:35], v[120:123], v[220:223], v[32:35]
	v_mfma_f32_16x16x32_bf16 v[28:31], v[144:147], v[220:223], v[28:31]
	v_mfma_f32_16x16x32_bf16 v[16:19], v[120:123], v[228:231], v[16:19]
	v_mfma_f32_16x16x32_bf16 v[12:15], v[144:147], v[228:231], v[12:15]
	s_setprio 0
	s_setprio 1
	v_mfma_f32_16x16x32_bf16 v[56:59], v[148:151], v[186:189], v[56:59]
	v_mfma_f32_16x16x32_bf16 v[52:55], v[156:159], v[186:189], v[52:55]
	v_mfma_f32_16x16x32_bf16 v[40:43], v[148:151], v[198:201], v[40:43]
	v_mfma_f32_16x16x32_bf16 v[36:39], v[156:159], v[198:201], v[36:39]
	v_mfma_f32_16x16x32_bf16 v[24:27], v[148:151], v[216:219], v[24:27]
	v_mfma_f32_16x16x32_bf16 v[20:23], v[156:159], v[216:219], v[20:23]
	v_mfma_f32_16x16x32_bf16 v[8:11], v[148:151], v[224:227], v[8:11]
	v_mfma_f32_16x16x32_bf16 v[4:7], v[156:159], v[224:227], v[4:7]
	v_mfma_f32_16x16x32_bf16 v[56:59], v[152:155], v[190:193], v[56:59]
	v_mfma_f32_16x16x32_bf16 v[52:55], v[182:185], v[190:193], v[52:55]
	v_mfma_f32_16x16x32_bf16 v[40:43], v[152:155], v[212:215], v[40:43]
	v_mfma_f32_16x16x32_bf16 v[36:39], v[182:185], v[212:215], v[36:39]
	v_mfma_f32_16x16x32_bf16 v[24:27], v[152:155], v[220:223], v[24:27]
	v_mfma_f32_16x16x32_bf16 v[20:23], v[182:185], v[220:223], v[20:23]
	v_mfma_f32_16x16x32_bf16 v[8:11], v[152:155], v[228:231], v[8:11]
	v_mfma_f32_16x16x32_bf16 v[4:7], v[182:185], v[228:231], v[4:7]
	s_setprio 0
	s_barrier
	s_add_i32 s57, s57, 2
	s_add_u32 s47, s47, 0x100
	s_addc_u32 s56, s56, 0
	s_cmp_gt_u32 s57, 61
	s_mov_b64 s[4:5], s[0:1]
	s_cbranch_scc0 .LBB0_590
	s_and_b64 vcc, exec, s[20:21]
	s_cbranch_vccz .LBB0_593
	s_barrier

; #define PG8_STAGE(bufoff, gbase, voff) do { _Pragma("unroll") for (int _i = 0; _i < 2; ++_i) \
;         __builtin_amdgcn_global_load_lds((const unsigned*)((const char*)(gbase) + (voff)[_i]), (PG8_LAS unsigned*)(lds + (bufoff) + ldsw + _i * 8192), 16, 0, 0); } while (0)
; #define PG8_LDA(dst, b, h) do { _Pragma("unroll") for (int m = 0; m < 4; ++m) _Pragma("unroll") for (int k = 0; k < 2; ++k) dst[m][k] = *(const PG8_LAS bf16x8*)(lds + PG8_SA(b, h) + aoff + m * 2048 + k * 1024); } while (0)
; #define PG8_LDB(dst, b, h) do { _Pragma("unroll") for (int n = 0; n < 2; ++n) _Pragma("unroll") for (int k = 0; k < 2; ++k) dst[n][k] = *(const PG8_LAS bf16x8*)(lds + PG8_SB(b, h) + boff + n * 2048 + k * 1024); } while (0)
; template <class Epi, class Sched, bool ALIGN_EPI = false, bool SP2 = false>
; __device__ __forceinline__ void gemm_phase(PG8_LAS unsigned char* lds, const Gemm g, const Sched& S, const Epi& E, int wave_s) {
;     ...
;             const bool last = (t == nt - 2);
;             const char* a1 = cA + (size_t)(t + 1) * kstep;
;             const char* a2 = last ? nA : cA + (size_t)(t + 2) * kstep; const char* b2 = last ? nB : cB + (size_t)(t + 2) * kstep;
;             const char* a3 = a2 + kstep; const char* b3 = b2 + kstep;
;             if (last && has_next) S.a_ready(nxt);
;             if constexpr (SP2) {
;             PG8_LDB(B0, 0, 0); PG8_LDB(B1, 0, 1); PG8_SCHED; PG8_LDA(At, 0, 0); PG8_STAGE(PG8_SA(1, 1), a1 + hstepA, voffA);
;             PG8_WAIT_V(8); PG8_WAIT_L(0); PG8_BAR; PG8_MMA(0, 0, At, B0); PG8_MMA(0, 1, At, B1); PG8_BAR; PG8_SCHED;
;             PG8_LDA(At, 0, 1); PG8_STAGE(PG8_SB(0, 0), b2, voffB); PG8_STAGE(PG8_SB(0, 1), b2 + hstepB, voffB); PG8_STAGE(PG8_SA(0, 0), a2, voffA);
;             PG8_WAIT_V(8); PG8_WAIT_L(0); PG8_BAR; PG8_MMA(1, 0, At, B0); PG8_MMA(1, 1, At, B1); PG8_BAR; PG8_SCHED;
;             PG8_LDB(B0, 1, 0); PG8_LDB(B1, 1, 1); PG8_SCHED; PG8_LDA(At, 1, 0); PG8_STAGE(PG8_SA(0, 1), a2 + hstepA, voffA);
;             PG8_WAIT_V(8); PG8_WAIT_L(0); PG8_BAR; PG8_MMA(0, 0, At, B0); PG8_MMA(0, 1, At, B1); PG8_BAR; PG8_SCHED;
;             PG8_LDA(At, 1, 1); PG8_STAGE(PG8_SB(1, 0), b3, voffB); PG8_STAGE(PG8_SB(1, 1), b3 + hstepB, voffB); PG8_STAGE(PG8_SA(1, 0), a3, voffA);
;             PG8_WAIT_V(8); PG8_WAIT_L(0); PG8_BAR; PG8_MMA(1, 0, At, B0); PG8_MMA(1, 1, At, B1); PG8_BAR; PG8_SCHED;
.LBB0_661:
	s_add_u32 s26, s18, 0xfff80080
	s_addc_u32 s27, s19, -1
	s_add_i32 s74, 0, 0x10000
	s_cmp_eq_u32 s67, 28
	s_cselect_b32 s43, s7, s27
	s_cselect_b32 s42, s57, s26
	s_cselect_b32 s27, s5, s66
	s_cselect_b32 s26, s58, s59
	s_add_i32 s76, 0, 0x14000
	s_waitcnt vmcnt(0) lgkmcnt(0)
	v_add_u32_e32 v120, s74, v211
	v_add_u32_e32 v160, s76, v211
	ds_read_b128 v[108:111], v120
	ds_read_b128 v[112:115], v120 offset:1024
	ds_read_b128 v[116:119], v120 offset:2048
	ds_read_b128 v[120:123], v120 offset:3072
	ds_read_b128 v[148:151], v160
	ds_read_b128 v[152:155], v160 offset:1024
	ds_read_b128 v[156:159], v160 offset:2048
	ds_read_b128 v[160:163], v160 offset:3072
	s_add_i32 m0, s47, 0xc000
	ds_read_b128 v[164:167], v213
	ds_read_b128 v[190:193], v213 offset:1024
	ds_read_b128 v[194:197], v213 offset:2048
	ds_read_b128 v[198:201], v213 offset:3072
	ds_read_b128 v[214:217], v213 offset:4096
	ds_read_b128 v[218:221], v213 offset:5120
	ds_read_b128 v[222:225], v213 offset:6144
	ds_read_b128 v[226:229], v213 offset:7168
	global_load_lds_dwordx4 v188, s[18:19]
	s_add_i32 m0, s47, 0xe000
	s_nop 0
	global_load_lds_dwordx4 v186, s[18:19]
	s_waitcnt vmcnt(8)
	s_waitcnt lgkmcnt(0)
	s_barrier
	s_setprio 1
	s_waitcnt lgkmcnt(0)
	v_mfma_f32_16x16x32_bf16 v[144:147], v[108:111], v[164:167], v[144:147]
	v_mfma_f32_16x16x32_bf16 v[140:143], v[116:119], v[164:167], v[140:143]
	v_mfma_f32_16x16x32_bf16 v[136:139], v[108:111], v[194:197], v[136:139]
	v_mfma_f32_16x16x32_bf16 v[132:135], v[116:119], v[194:197], v[132:135]
	v_mfma_f32_16x16x32_bf16 v[96:99], v[108:111], v[214:217], v[96:99]
	v_mfma_f32_16x16x32_bf16 v[92:95], v[116:119], v[214:217], v[92:95]
	v_mfma_f32_16x16x32_bf16 v[80:83], v[108:111], v[222:225], v[80:83]
	v_mfma_f32_16x16x32_bf16 v[76:79], v[116:119], v[222:225], v[76:79]
	v_mfma_f32_16x16x32_bf16 v[144:147], v[112:115], v[190:193], v[144:147]
	v_mfma_f32_16x16x32_bf16 v[140:143], v[120:123], v[190:193], v[140:143]
	v_mfma_f32_16x16x32_bf16 v[136:139], v[112:115], v[198:201], v[136:139]
	v_mfma_f32_16x16x32_bf16 v[132:135], v[120:123], v[198:201], v[132:135]
	v_mfma_f32_16x16x32_bf16 v[96:99], v[112:115], v[218:221], v[96:99]
	v_mfma_f32_16x16x32_bf16 v[92:95], v[120:123], v[218:221], v[92:95]
	v_mfma_f32_16x16x32_bf16 v[80:83], v[112:115], v[226:229], v[80:83]
	v_mfma_f32_16x16x32_bf16 v[76:79], v[120:123], v[226:229], v[76:79]
	s_setprio 0
	s_setprio 1
	v_mfma_f32_16x16x32_bf16 v[128:131], v[148:151], v[164:167], v[128:131]
	v_mfma_f32_16x16x32_bf16 v[124:127], v[156:159], v[164:167], v[124:127]
	v_mfma_f32_16x16x32_bf16 v[104:107], v[148:151], v[194:197], v[104:107]
	v_mfma_f32_16x16x32_bf16 v[100:103], v[156:159], v[194:197], v[100:103]
	v_mfma_f32_16x16x32_bf16 v[88:91], v[148:151], v[214:217], v[88:91]
	v_mfma_f32_16x16x32_bf16 v[84:87], v[156:159], v[214:217], v[84:87]
	v_mfma_f32_16x16x32_bf16 v[72:75], v[148:151], v[222:225], v[72:75]
	v_mfma_f32_16x16x32_bf16 v[68:71], v[156:159], v[222:225], v[68:71]
	v_mfma_f32_16x16x32_bf16 v[128:131], v[152:155], v[190:193], v[128:131]
	v_mfma_f32_16x16x32_bf16 v[124:127], v[160:163], v[190:193], v[124:127]
	v_mfma_f32_16x16x32_bf16 v[104:107], v[152:155], v[198:201], v[104:107]
	v_mfma_f32_16x16x32_bf16 v[100:103], v[160:163], v[198:201], v[100:103]
	v_mfma_f32_16x16x32_bf16 v[88:91], v[152:155], v[218:221], v[88:91]
	v_mfma_f32_16x16x32_bf16 v[84:87], v[160:163], v[218:221], v[84:87]
	v_mfma_f32_16x16x32_bf16 v[72:75], v[152:155], v[226:229], v[72:75]
	v_mfma_f32_16x16x32_bf16 v[68:71], v[160:163], v[226:229], v[68:71]
	s_setprio 0
	s_barrier
	s_add_i32 s74, s74, s46
	s_add_u32 s98, s26, s60
	s_addc_u32 s99, s27, s61
	s_mov_b32 m0, s74
	ds_read_b128 v[164:167], v213 offset:16384
	ds_read_b128 v[190:193], v213 offset:17408
	ds_read_b128 v[194:197], v213 offset:18432
	ds_read_b128 v[198:201], v213 offset:19456
	ds_read_b128 v[214:217], v213 offset:20480
	ds_read_b128 v[218:221], v213 offset:21504
	ds_read_b128 v[222:225], v213 offset:22528
	ds_read_b128 v[226:229], v213 offset:23552
	global_load_lds_dwordx4 v2, s[26:27]
	s_add_i32 m0, s74, 0x2000
	s_add_u32 s74, s26, 0x80000
	s_addc_u32 s75, s27, 0
	s_add_i32 s76, s76, s46
	global_load_lds_dwordx4 v0, s[26:27]
	s_mov_b32 m0, s76
	s_add_u32 s100, s42, s60
	s_addc_u32 s101, s43, s61
	s_nop 0
	global_load_lds_dwordx4 v2, s[74:75]
	s_add_i32 m0, s76, 0x2000
	s_nop 0
	global_load_lds_dwordx4 v0, s[74:75]
	s_mov_b32 m0, s47
	s_nop 0
	global_load_lds_dwordx4 v184, s[42:43]
	s_mov_b32 m0, s48
	s_nop 0
	global_load_lds_dwordx4 v182, s[42:43]
	s_waitcnt vmcnt(8)
	s_waitcnt lgkmcnt(0)
	s_barrier
; #define PG8_STAGE(bufoff, gbase, voff) do { _Pragma("unroll") for (int _i = 0; _i < 2; ++_i) \
;         __builtin_amdgcn_global_load_lds((const unsigned*)((const char*)(gbase) + (voff)[_i]), (PG8_LAS unsigned*)(lds + (bufoff) + ldsw + _i * 8192), 16, 0, 0); } while (0)
; #define PG8_LDA(dst, b, h) do { _Pragma("unroll") for (int m = 0; m < 4; ++m) _Pragma("unroll") for (int k = 0; k < 2; ++k) dst[m][k] = *(const PG8_LAS bf16x8*)(lds + PG8_SA(b, h) + aoff + m * 2048 + k * 1024); } while (0)
; #define PG8_LDB(dst, b, h) do { _Pragma("unroll") for (int n = 0; n < 2; ++n) _Pragma("unroll") for (int k = 0; k < 2; ++k) dst[n][k] = *(const PG8_LAS bf16x8*)(lds + PG8_SB(b, h) + boff + n * 2048 + k * 1024); } while (0)
; #define PG8_MMA(ai, bj, At, Bt) do { __builtin_amdgcn_s_setprio(1); _Pragma("unroll") for (int m = 0; m < 4; ++m) _Pragma("unroll") for (int n = 0; n < 2; ++n) _Pragma("unroll") for (int k = 0; k < 2; ++k) \
;         acc[ai][bj][m][n] = __builtin_amdgcn_mfma_f32_16x16x32_bf16(Bt[n][k], At[m][k], acc[ai][bj][m][n], 0, 0, 0); __builtin_amdgcn_s_setprio(0); } while (0)
; #define PG8_BAR __builtin_amdgcn_s_barrier()
; template <class Epi, class Sched, bool ALIGN_EPI = false, bool SP2 = false>
; __device__ __forceinline__ void gemm_phase(PG8_LAS unsigned char* lds, const Gemm g, const Sched& S, const Epi& E, int wave_s) {
;     ...
;             PG8_LDB(B0, 0, 0); PG8_LDB(B1, 0, 1); PG8_SCHED; PG8_LDA(At, 0, 0); PG8_STAGE(PG8_SA(1, 1), a1 + hstepA, voffA);
;             PG8_WAIT_V(8); PG8_WAIT_L(0); PG8_BAR; PG8_MMA(0, 0, At, B0); PG8_MMA(0, 1, At, B1); PG8_BAR; PG8_SCHED;
;             PG8_LDA(At, 0, 1); PG8_STAGE(PG8_SB(0, 0), b2, voffB); PG8_STAGE(PG8_SB(0, 1), b2 + hstepB, voffB); PG8_STAGE(PG8_SA(0, 0), a2, voffA);
;             PG8_WAIT_V(8); PG8_WAIT_L(0); PG8_BAR; PG8_MMA(1, 0, At, B0); PG8_MMA(1, 1, At, B1); PG8_BAR; PG8_SCHED;
;             PG8_LDB(B0, 1, 0); PG8_LDB(B1, 1, 1); PG8_SCHED; PG8_LDA(At, 1, 0); PG8_STAGE(PG8_SA(0, 1), a2 + hstepA, voffA);
;             PG8_WAIT_V(8); PG8_WAIT_L(0); PG8_BAR; PG8_MMA(0, 0, At, B0); PG8_MMA(0, 1, At, B1); PG8_BAR; PG8_SCHED;
;             PG8_LDA(At, 1, 1); PG8_STAGE(PG8_SB(1, 0), b3, voffB); PG8_STAGE(PG8_SB(1, 1), b3 + hstepB, voffB); PG8_STAGE(PG8_SA(1, 0), a3, voffA);
;             PG8_WAIT_V(8); PG8_WAIT_L(0); PG8_BAR; PG8_MMA(1, 0, At, B0); PG8_MMA(1, 1, At, B1); PG8_BAR; PG8_SCHED;
	s_setprio 1
	s_waitcnt lgkmcnt(0)
	v_mfma_f32_16x16x32_bf16 v[64:67], v[108:111], v[164:167], v[64:67]
	v_mfma_f32_16x16x32_bf16 v[60:63], v[116:119], v[164:167], v[60:63]
	v_mfma_f32_16x16x32_bf16 v[48:51], v[108:111], v[194:197], v[48:51]
	v_mfma_f32_16x16x32_bf16 v[44:47], v[116:119], v[194:197], v[44:47]
	v_mfma_f32_16x16x32_bf16 v[32:35], v[108:111], v[214:217], v[32:35]
	v_mfma_f32_16x16x32_bf16 v[28:31], v[116:119], v[214:217], v[28:31]
	v_mfma_f32_16x16x32_bf16 v[16:19], v[108:111], v[222:225], v[16:19]
	v_mfma_f32_16x16x32_bf16 v[12:15], v[116:119], v[222:225], v[12:15]
	v_mfma_f32_16x16x32_bf16 v[64:67], v[112:115], v[190:193], v[64:67]
	v_mfma_f32_16x16x32_bf16 v[60:63], v[120:123], v[190:193], v[60:63]
	v_mfma_f32_16x16x32_bf16 v[48:51], v[112:115], v[198:201], v[48:51]
	v_mfma_f32_16x16x32_bf16 v[44:47], v[120:123], v[198:201], v[44:47]
	v_mfma_f32_16x16x32_bf16 v[32:35], v[112:115], v[218:221], v[32:35]
	v_mfma_f32_16x16x32_bf16 v[28:31], v[120:123], v[218:221], v[28:31]
	v_mfma_f32_16x16x32_bf16 v[16:19], v[112:115], v[226:229], v[16:19]
	v_mfma_f32_16x16x32_bf16 v[12:15], v[120:123], v[226:229], v[12:15]
	s_setprio 0
	s_setprio 1
	v_mfma_f32_16x16x32_bf16 v[56:59], v[148:151], v[164:167], v[56:59]
	v_mfma_f32_16x16x32_bf16 v[52:55], v[156:159], v[164:167], v[52:55]
	v_mfma_f32_16x16x32_bf16 v[40:43], v[148:151], v[194:197], v[40:43]
	v_mfma_f32_16x16x32_bf16 v[36:39], v[156:159], v[194:197], v[36:39]
	v_mfma_f32_16x16x32_bf16 v[24:27], v[148:151], v[214:217], v[24:27]
	v_mfma_f32_16x16x32_bf16 v[20:23], v[156:159], v[214:217], v[20:23]
	v_mfma_f32_16x16x32_bf16 v[8:11], v[148:151], v[222:225], v[8:11]
	v_mfma_f32_16x16x32_bf16 v[4:7], v[156:159], v[222:225], v[4:7]
	v_mfma_f32_16x16x32_bf16 v[56:59], v[152:155], v[190:193], v[56:59]
	v_mfma_f32_16x16x32_bf16 v[52:55], v[160:163], v[190:193], v[52:55]
	v_mfma_f32_16x16x32_bf16 v[40:43], v[152:155], v[198:201], v[40:43]
	v_mfma_f32_16x16x32_bf16 v[36:39], v[160:163], v[198:201], v[36:39]
	v_mfma_f32_16x16x32_bf16 v[24:27], v[152:155], v[218:221], v[24:27]
	v_mfma_f32_16x16x32_bf16 v[20:23], v[160:163], v[218:221], v[20:23]
	v_mfma_f32_16x16x32_bf16 v[8:11], v[152:155], v[226:229], v[8:11]
	v_mfma_f32_16x16x32_bf16 v[4:7], v[160:163], v[226:229], v[4:7]
	s_setprio 0
	s_barrier
	s_add_i32 s74, 0, 0x18000
	s_add_i32 s75, 0, 0x1c000
	v_add_u32_e32 v120, s74, v211
	v_add_u32_e32 v160, s75, v211
	ds_read_b128 v[108:111], v120
	ds_read_b128 v[112:115], v120 offset:1024
	ds_read_b128 v[116:119], v120 offset:2048
	ds_read_b128 v[120:123], v120 offset:3072
	ds_read_b128 v[148:151], v160
	ds_read_b128 v[152:155], v160 offset:1024
	ds_read_b128 v[156:159], v160 offset:2048
	ds_read_b128 v[160:163], v160 offset:3072
	s_add_u32 s42, s42, 0x80000
	s_addc_u32 s43, s43, 0
	s_mov_b32 m0, s49
	ds_read_b128 v[164:167], v213 offset:32768
	ds_read_b128 v[190:193], v213 offset:33792
	ds_read_b128 v[194:197], v213 offset:34816
	ds_read_b128 v[198:201], v213 offset:35840
	ds_read_b128 v[214:217], v213 offset:36864
	ds_read_b128 v[218:221], v213 offset:37888
	ds_read_b128 v[222:225], v213 offset:38912
	ds_read_b128 v[226:229], v213 offset:39936
	global_load_lds_dwordx4 v184, s[42:43]
	s_mov_b32 m0, s50
	s_nop 0
	global_load_lds_dwordx4 v182, s[42:43]
	s_waitcnt vmcnt(8)
	s_waitcnt lgkmcnt(0)
	s_barrier
	s_setprio 1
	s_waitcnt lgkmcnt(0)
	v_mfma_f32_16x16x32_bf16 v[144:147], v[108:111], v[164:167], v[144:147]
	v_mfma_f32_16x16x32_bf16 v[140:143], v[116:119], v[164:167], v[140:143]
	v_mfma_f32_16x16x32_bf16 v[136:139], v[108:111], v[194:197], v[136:139]
	v_mfma_f32_16x16x32_bf16 v[132:135], v[116:119], v[194:197], v[132:135]
	v_mfma_f32_16x16x32_bf16 v[96:99], v[108:111], v[214:217], v[96:99]
	v_mfma_f32_16x16x32_bf16 v[92:95], v[116:119], v[214:217], v[92:95]
	v_mfma_f32_16x16x32_bf16 v[80:83], v[108:111], v[222:225], v[80:83]
	v_mfma_f32_16x16x32_bf16 v[76:79], v[116:119], v[222:225], v[76:79]
	v_mfma_f32_16x16x32_bf16 v[144:147], v[112:115], v[190:193], v[144:147]
	v_mfma_f32_16x16x32_bf16 v[140:143], v[120:123], v[190:193], v[140:143]
	v_mfma_f32_16x16x32_bf16 v[136:139], v[112:115], v[198:201], v[136:139]
	v_mfma_f32_16x16x32_bf16 v[132:135], v[120:123], v[198:201], v[132:135]
	v_mfma_f32_16x16x32_bf16 v[96:99], v[112:115], v[218:221], v[96:99]
	v_mfma_f32_16x16x32_bf16 v[92:95], v[120:123], v[218:221], v[92:95]
	v_mfma_f32_16x16x32_bf16 v[80:83], v[112:115], v[226:229], v[80:83]
	v_mfma_f32_16x16x32_bf16 v[76:79], v[120:123], v[226:229], v[76:79]
	s_setprio 0
	s_setprio 1
	v_mfma_f32_16x16x32_bf16 v[128:131], v[148:151], v[164:167], v[128:131]
	v_mfma_f32_16x16x32_bf16 v[124:127], v[156:159], v[164:167], v[124:127]
	v_mfma_f32_16x16x32_bf16 v[104:107], v[148:151], v[194:197], v[104:107]
	v_mfma_f32_16x16x32_bf16 v[100:103], v[156:159], v[194:197], v[100:103]
	v_mfma_f32_16x16x32_bf16 v[88:91], v[148:151], v[214:217], v[88:91]
	v_mfma_f32_16x16x32_bf16 v[84:87], v[156:159], v[214:217], v[84:87]
	v_mfma_f32_16x16x32_bf16 v[72:75], v[148:151], v[222:225], v[72:75]
	v_mfma_f32_16x16x32_bf16 v[68:71], v[156:159], v[222:225], v[68:71]
	v_mfma_f32_16x16x32_bf16 v[128:131], v[152:155], v[190:193], v[128:131]
	v_mfma_f32_16x16x32_bf16 v[124:127], v[160:163], v[190:193], v[124:127]
	v_mfma_f32_16x16x32_bf16 v[104:107], v[152:155], v[198:201], v[104:107]
	v_mfma_f32_16x16x32_bf16 v[100:103], v[160:163], v[198:201], v[100:103]
	v_mfma_f32_16x16x32_bf16 v[88:91], v[152:155], v[218:221], v[88:91]
	v_mfma_f32_16x16x32_bf16 v[84:87], v[160:163], v[218:221], v[84:87]
	v_mfma_f32_16x16x32_bf16 v[72:75], v[152:155], v[226:229], v[72:75]
	v_mfma_f32_16x16x32_bf16 v[68:71], v[160:163], v[226:229], v[68:71]
	s_setprio 0
	s_barrier
; #define PG8_STAGE(bufoff, gbase, voff) do { _Pragma("unroll") for (int _i = 0; _i < 2; ++_i) \
;         __builtin_amdgcn_global_load_lds((const unsigned*)((const char*)(gbase) + (voff)[_i]), (PG8_LAS unsigned*)(lds + (bufoff) + ldsw + _i * 8192), 16, 0, 0); } while (0)
; #define PG8_LDA(dst, b, h) do { _Pragma("unroll") for (int m = 0; m < 4; ++m) _Pragma("unroll") for (int k = 0; k < 2; ++k) dst[m][k] = *(const PG8_LAS bf16x8*)(lds + PG8_SA(b, h) + aoff + m * 2048 + k * 1024); } while (0)
; #define PG8_WAIT_V(n) asm volatile("s_waitcnt vmcnt(" #n ")" ::: "memory")
; #define PG8_WAIT_L(n) asm volatile("s_waitcnt lgkmcnt(" #n ")" ::: "memory")
; #define PG8_BAR __builtin_amdgcn_s_barrier()
; template <class Epi, class Sched, bool ALIGN_EPI = false, bool SP2 = false>
; __device__ __forceinline__ void gemm_phase(PG8_LAS unsigned char* lds, const Gemm g, const Sched& S, const Epi& E, int wave_s) {
;     ...
;         for (int t = 0; t < nt; t += 2) {
;             const bool last = (t == nt - 2);
;             const char* a1 = cA + (size_t)(t + 1) * kstep;
;             const char* a2 = last ? nA : cA + (size_t)(t + 2) * kstep; const char* b2 = last ? nB : cB + (size_t)(t + 2) * kstep;
;             const char* a3 = a2 + kstep; const char* b3 = b2 + kstep;
;             if (last && has_next) S.a_ready(nxt);
;             if constexpr (SP2) {
;             PG8_LDB(B0, 0, 0); PG8_LDB(B1, 0, 1); PG8_SCHED; PG8_LDA(At, 0, 0); PG8_STAGE(PG8_SA(1, 1), a1 + hstepA, voffA);
;             PG8_WAIT_V(8); PG8_WAIT_L(0); PG8_BAR; PG8_MMA(0, 0, At, B0); PG8_MMA(0, 1, At, B1); PG8_BAR; PG8_SCHED;
;             PG8_LDA(At, 0, 1); PG8_STAGE(PG8_SB(0, 0), b2, voffB); PG8_STAGE(PG8_SB(0, 1), b2 + hstepB, voffB); PG8_STAGE(PG8_SA(0, 0), a2, voffA);
;             PG8_WAIT_V(8); PG8_WAIT_L(0); PG8_BAR; PG8_MMA(1, 0, At, B0); PG8_MMA(1, 1, At, B1); PG8_BAR; PG8_SCHED;
;             PG8_LDB(B0, 1, 0); PG8_LDB(B1, 1, 1); PG8_SCHED; PG8_LDA(At, 1, 0); PG8_STAGE(PG8_SA(0, 1), a2 + hstepA, voffA);
;             PG8_WAIT_V(8); PG8_WAIT_L(0); PG8_BAR; PG8_MMA(0, 0, At, B0); PG8_MMA(0, 1, At, B1); PG8_BAR; PG8_SCHED;
;             PG8_LDA(At, 1, 1); PG8_STAGE(PG8_SB(1, 0), b3, voffB); PG8_STAGE(PG8_SB(1, 1), b3 + hstepB, voffB); PG8_STAGE(PG8_SA(1, 0), a3, voffA);
;             PG8_WAIT_V(8); PG8_WAIT_L(0); PG8_BAR; PG8_MMA(1, 0, At, B0); PG8_MMA(1, 1, At, B1); PG8_BAR; PG8_SCHED;
	s_add_i32 s42, s74, s46
	s_mov_b32 m0, s42
	ds_read_b128 v[164:167], v213 offset:49152
	ds_read_b128 v[190:193], v213 offset:50176
	ds_read_b128 v[194:197], v213 offset:51200
	ds_read_b128 v[198:201], v213 offset:52224
	ds_read_b128 v[214:217], v213 offset:53248
	ds_read_b128 v[218:221], v213 offset:54272
	ds_read_b128 v[222:225], v213 offset:55296
	ds_read_b128 v[226:229], v213 offset:56320
	global_load_lds_dwordx4 v2, s[98:99]
	s_add_i32 m0, s42, 0x2000
	s_add_u32 s26, s26, 0x80080
	s_addc_u32 s27, s27, 0
	s_add_i32 s42, s75, s46
	global_load_lds_dwordx4 v0, s[98:99]
	s_mov_b32 m0, s42
	s_nop 0
	global_load_lds_dwordx4 v2, s[26:27]
	s_add_i32 m0, s42, 0x2000
	s_nop 0
	global_load_lds_dwordx4 v0, s[26:27]
	s_mov_b32 m0, s54
	s_nop 0
	global_load_lds_dwordx4 v184, s[100:101]
	s_mov_b32 m0, s55
	s_nop 0
	global_load_lds_dwordx4 v182, s[100:101]
	s_waitcnt vmcnt(8)
	s_waitcnt lgkmcnt(0)
	s_barrier
	s_setprio 1
	s_waitcnt lgkmcnt(0)
	v_mfma_f32_16x16x32_bf16 v[64:67], v[108:111], v[164:167], v[64:67]
	v_mfma_f32_16x16x32_bf16 v[60:63], v[116:119], v[164:167], v[60:63]
	v_mfma_f32_16x16x32_bf16 v[48:51], v[108:111], v[194:197], v[48:51]
	v_mfma_f32_16x16x32_bf16 v[44:47], v[116:119], v[194:197], v[44:47]
	v_mfma_f32_16x16x32_bf16 v[32:35], v[108:111], v[214:217], v[32:35]
	v_mfma_f32_16x16x32_bf16 v[28:31], v[116:119], v[214:217], v[28:31]
	v_mfma_f32_16x16x32_bf16 v[16:19], v[108:111], v[222:225], v[16:19]
	v_mfma_f32_16x16x32_bf16 v[12:15], v[116:119], v[222:225], v[12:15]
	v_mfma_f32_16x16x32_bf16 v[64:67], v[112:115], v[190:193], v[64:67]
	v_mfma_f32_16x16x32_bf16 v[60:63], v[120:123], v[190:193], v[60:63]
	v_mfma_f32_16x16x32_bf16 v[48:51], v[112:115], v[198:201], v[48:51]
	v_mfma_f32_16x16x32_bf16 v[44:47], v[120:123], v[198:201], v[44:47]
	v_mfma_f32_16x16x32_bf16 v[32:35], v[112:115], v[218:221], v[32:35]
	v_mfma_f32_16x16x32_bf16 v[28:31], v[120:123], v[218:221], v[28:31]
	v_mfma_f32_16x16x32_bf16 v[16:19], v[112:115], v[226:229], v[16:19]
	v_mfma_f32_16x16x32_bf16 v[12:15], v[120:123], v[226:229], v[12:15]
	s_setprio 0
	s_setprio 1
	v_mfma_f32_16x16x32_bf16 v[56:59], v[148:151], v[164:167], v[56:59]
	v_mfma_f32_16x16x32_bf16 v[52:55], v[156:159], v[164:167], v[52:55]
	v_mfma_f32_16x16x32_bf16 v[40:43], v[148:151], v[194:197], v[40:43]
	v_mfma_f32_16x16x32_bf16 v[36:39], v[156:159], v[194:197], v[36:39]
	v_mfma_f32_16x16x32_bf16 v[24:27], v[148:151], v[214:217], v[24:27]
	v_mfma_f32_16x16x32_bf16 v[20:23], v[156:159], v[214:217], v[20:23]
	v_mfma_f32_16x16x32_bf16 v[8:11], v[148:151], v[222:225], v[8:11]
	v_mfma_f32_16x16x32_bf16 v[4:7], v[156:159], v[222:225], v[4:7]
	v_mfma_f32_16x16x32_bf16 v[56:59], v[152:155], v[190:193], v[56:59]
	v_mfma_f32_16x16x32_bf16 v[52:55], v[160:163], v[190:193], v[52:55]
	v_mfma_f32_16x16x32_bf16 v[40:43], v[152:155], v[198:201], v[40:43]
	v_mfma_f32_16x16x32_bf16 v[36:39], v[160:163], v[198:201], v[36:39]
	v_mfma_f32_16x16x32_bf16 v[24:27], v[152:155], v[218:221], v[24:27]
	v_mfma_f32_16x16x32_bf16 v[20:23], v[160:163], v[218:221], v[20:23]
	v_mfma_f32_16x16x32_bf16 v[8:11], v[152:155], v[226:229], v[8:11]
	v_mfma_f32_16x16x32_bf16 v[4:7], v[160:163], v[226:229], v[4:7]
	s_setprio 0
	s_barrier
	s_add_i32 s67, s67, 2
	s_add_u32 s59, s59, 0x100
	s_addc_u32 s66, s66, 0
	s_add_u32 s18, s18, 0x100
	s_addc_u32 s19, s19, 0
	s_cmp_gt_u32 s67, 29
	s_cbranch_scc0 .LBB0_661
	s_and_b64 vcc, exec, s[38:39]
	s_cbranch_vccz .LBB0_664
	s_barrier

; #define PG8_STAGE(bufoff, gbase, voff) do { _Pragma("unroll") for (int _i = 0; _i < 2; ++_i) \
;         __builtin_amdgcn_global_load_lds((const unsigned*)((const char*)(gbase) + (voff)[_i]), (PG8_LAS unsigned*)(lds + (bufoff) + ldsw + _i * 8192), 16, 0, 0); } while (0)
; #define PG8_LDA(dst, b, h) do { _Pragma("unroll") for (int m = 0; m < 4; ++m) _Pragma("unroll") for (int k = 0; k < 2; ++k) dst[m][k] = *(const PG8_LAS bf16x8*)(lds + PG8_SA(b, h) + aoff + m * 2048 + k * 1024); } while (0)
; #define PG8_LDB(dst, b, h) do { _Pragma("unroll") for (int n = 0; n < 2; ++n) _Pragma("unroll") for (int k = 0; k < 2; ++k) dst[n][k] = *(const PG8_LAS bf16x8*)(lds + PG8_SB(b, h) + boff + n * 2048 + k * 1024); } while (0)
; template <class Epi, class Sched, bool ALIGN_EPI = false, bool SP2 = false>
; __device__ __forceinline__ void gemm_phase(PG8_LAS unsigned char* lds, const Gemm g, const Sched& S, const Epi& E, int wave_s) {
;     ...
;             const bool last = (t == nt - 2);
;             const char* a1 = cA + (size_t)(t + 1) * kstep;
;             const char* a2 = last ? nA : cA + (size_t)(t + 2) * kstep; const char* b2 = last ? nB : cB + (size_t)(t + 2) * kstep;
;             const char* a3 = a2 + kstep; const char* b3 = b2 + kstep;
;             if (last && has_next) S.a_ready(nxt);
;             if constexpr (SP2) {
;             PG8_LDB(B0, 0, 0); PG8_LDB(B1, 0, 1); PG8_SCHED; PG8_LDA(At, 0, 0); PG8_STAGE(PG8_SA(1, 1), a1 + hstepA, voffA);
;             PG8_WAIT_V(8); PG8_WAIT_L(0); PG8_BAR; PG8_MMA(0, 0, At, B0); PG8_MMA(0, 1, At, B1); PG8_BAR; PG8_SCHED;
;             PG8_LDA(At, 0, 1); PG8_STAGE(PG8_SB(0, 0), b2, voffB); PG8_STAGE(PG8_SB(0, 1), b2 + hstepB, voffB); PG8_STAGE(PG8_SA(0, 0), a2, voffA);
;             PG8_WAIT_V(8); PG8_WAIT_L(0); PG8_BAR; PG8_MMA(1, 0, At, B0); PG8_MMA(1, 1, At, B1); PG8_BAR; PG8_SCHED;
;             PG8_LDB(B0, 1, 0); PG8_LDB(B1, 1, 1); PG8_SCHED; PG8_LDA(At, 1, 0); PG8_STAGE(PG8_SA(0, 1), a2 + hstepA, voffA);
;             PG8_WAIT_V(8); PG8_WAIT_L(0); PG8_BAR; PG8_MMA(0, 0, At, B0); PG8_MMA(0, 1, At, B1); PG8_BAR; PG8_SCHED;
;             PG8_LDA(At, 1, 1); PG8_STAGE(PG8_SB(1, 0), b3, voffB); PG8_STAGE(PG8_SB(1, 1), b3 + hstepB, voffB); PG8_STAGE(PG8_SA(1, 0), a3, voffA);
;             PG8_WAIT_V(8); PG8_WAIT_L(0); PG8_BAR; PG8_MMA(1, 0, At, B0); PG8_MMA(1, 1, At, B1); PG8_BAR; PG8_SCHED;
.LBB0_790:
	s_add_u32 s26, s18, 0xfff80080
	s_addc_u32 s27, s19, -1
	s_add_i32 s56, 0, 0x10000
	s_cmp_eq_u32 s55, 28
	s_cselect_b32 s39, s21, s27
	s_cselect_b32 s38, s51, s26
	v_add_u32_e32 v140, s56, v143
	s_cselect_b32 s27, s17, s54
	s_cselect_b32 s26, s52, s53
	s_add_i32 s58, 0, 0x14000
	ds_read_b128 v[146:149], v140
	ds_read_b128 v[150:153], v140 offset:1024
	ds_read_b128 v[154:157], v140 offset:2048
	ds_read_b128 v[158:161], v140 offset:3072
	v_add_u32_e32 v140, s58, v143
	ds_read_b128 v[162:165], v140
	ds_read_b128 v[182:185], v140 offset:1024
	ds_read_b128 v[186:189], v140 offset:2048
	ds_read_b128 v[190:193], v140 offset:3072
	s_add_i32 m0, s43, 0xc000
	ds_read_b128 v[194:197], v145
	ds_read_b128 v[198:201], v145 offset:1024
	ds_read_b128 v[212:215], v145 offset:2048
	ds_read_b128 v[216:219], v145 offset:3072
	ds_read_b128 v[220:223], v145 offset:4096
	ds_read_b128 v[224:227], v145 offset:5120
	ds_read_b128 v[228:231], v145 offset:6144
	ds_read_b128 v[232:235], v145 offset:7168
	global_load_lds_dwordx4 v138, s[18:19]
	s_add_i32 m0, s43, 0xe000
	s_nop 0
	global_load_lds_dwordx4 v136, s[18:19]
	s_waitcnt vmcnt(8)
	s_waitcnt lgkmcnt(0)
	s_barrier
	s_setprio 1
	s_waitcnt lgkmcnt(0)
	v_mfma_f32_16x16x32_bf16 v[128:131], v[146:149], v[194:197], v[128:131]
	v_mfma_f32_16x16x32_bf16 v[120:123], v[154:157], v[194:197], v[120:123]
	v_mfma_f32_16x16x32_bf16 v[112:115], v[146:149], v[212:215], v[112:115]
	v_mfma_f32_16x16x32_bf16 v[104:107], v[154:157], v[212:215], v[104:107]
	v_mfma_f32_16x16x32_bf16 v[96:99], v[146:149], v[220:223], v[96:99]
	v_mfma_f32_16x16x32_bf16 v[88:91], v[154:157], v[220:223], v[88:91]
	v_mfma_f32_16x16x32_bf16 v[80:83], v[146:149], v[228:231], v[80:83]
	v_mfma_f32_16x16x32_bf16 v[72:75], v[154:157], v[228:231], v[72:75]
	v_mfma_f32_16x16x32_bf16 v[128:131], v[150:153], v[198:201], v[128:131]
	v_mfma_f32_16x16x32_bf16 v[120:123], v[158:161], v[198:201], v[120:123]
	v_mfma_f32_16x16x32_bf16 v[112:115], v[150:153], v[216:219], v[112:115]
	v_mfma_f32_16x16x32_bf16 v[104:107], v[158:161], v[216:219], v[104:107]
	v_mfma_f32_16x16x32_bf16 v[96:99], v[150:153], v[224:227], v[96:99]
	v_mfma_f32_16x16x32_bf16 v[88:91], v[158:161], v[224:227], v[88:91]
	v_mfma_f32_16x16x32_bf16 v[80:83], v[150:153], v[232:235], v[80:83]
	v_mfma_f32_16x16x32_bf16 v[72:75], v[158:161], v[232:235], v[72:75]
	s_setprio 0
	s_setprio 1
	v_mfma_f32_16x16x32_bf16 v[124:127], v[162:165], v[194:197], v[124:127]
	v_mfma_f32_16x16x32_bf16 v[116:119], v[186:189], v[194:197], v[116:119]
	v_mfma_f32_16x16x32_bf16 v[108:111], v[162:165], v[212:215], v[108:111]
	v_mfma_f32_16x16x32_bf16 v[100:103], v[186:189], v[212:215], v[100:103]
	v_mfma_f32_16x16x32_bf16 v[92:95], v[162:165], v[220:223], v[92:95]
	v_mfma_f32_16x16x32_bf16 v[84:87], v[186:189], v[220:223], v[84:87]
	v_mfma_f32_16x16x32_bf16 v[76:79], v[162:165], v[228:231], v[76:79]
	v_mfma_f32_16x16x32_bf16 v[68:71], v[186:189], v[228:231], v[68:71]
	v_mfma_f32_16x16x32_bf16 v[124:127], v[182:185], v[198:201], v[124:127]
	v_mfma_f32_16x16x32_bf16 v[116:119], v[190:193], v[198:201], v[116:119]
	v_mfma_f32_16x16x32_bf16 v[108:111], v[182:185], v[216:219], v[108:111]
	v_mfma_f32_16x16x32_bf16 v[100:103], v[190:193], v[216:219], v[100:103]
	v_mfma_f32_16x16x32_bf16 v[92:95], v[182:185], v[224:227], v[92:95]
	v_mfma_f32_16x16x32_bf16 v[84:87], v[190:193], v[224:227], v[84:87]
	v_mfma_f32_16x16x32_bf16 v[76:79], v[182:185], v[232:235], v[76:79]
	v_mfma_f32_16x16x32_bf16 v[68:71], v[190:193], v[232:235], v[68:71]
	s_setprio 0
	s_barrier
	s_add_i32 s56, s56, s42
	s_add_u32 s98, s26, s60
	s_addc_u32 s99, s27, s61
	s_mov_b32 m0, s56
	ds_read_b128 v[194:197], v145 offset:16384
	ds_read_b128 v[198:201], v145 offset:17408
	ds_read_b128 v[212:215], v145 offset:18432
	ds_read_b128 v[216:219], v145 offset:19456
	ds_read_b128 v[220:223], v145 offset:20480
	ds_read_b128 v[224:227], v145 offset:21504
	ds_read_b128 v[228:231], v145 offset:22528
	ds_read_b128 v[232:235], v145 offset:23552
	global_load_lds_dwordx4 v2, s[26:27]
	s_add_i32 m0, s56, 0x2000
	s_add_u32 s56, s26, 0x80000
	s_addc_u32 s57, s27, 0
	s_add_i32 s58, s58, s42
	global_load_lds_dwordx4 v0, s[26:27]
	s_mov_b32 m0, s58
	s_add_u32 s100, s38, s60
	s_addc_u32 s101, s39, s61
	s_nop 0
	global_load_lds_dwordx4 v2, s[56:57]
	s_add_i32 m0, s58, 0x2000
	s_nop 0
	global_load_lds_dwordx4 v0, s[56:57]
	s_mov_b32 m0, s43
	s_nop 0
	global_load_lds_dwordx4 v134, s[38:39]
	s_mov_b32 m0, s44
	s_nop 0
	global_load_lds_dwordx4 v132, s[38:39]
	s_waitcnt vmcnt(8)
	s_waitcnt lgkmcnt(0)
	s_barrier
; #define PG8_STAGE(bufoff, gbase, voff) do { _Pragma("unroll") for (int _i = 0; _i < 2; ++_i) \
;         __builtin_amdgcn_global_load_lds((const unsigned*)((const char*)(gbase) + (voff)[_i]), (PG8_LAS unsigned*)(lds + (bufoff) + ldsw + _i * 8192), 16, 0, 0); } while (0)
; #define PG8_LDA(dst, b, h) do { _Pragma("unroll") for (int m = 0; m < 4; ++m) _Pragma("unroll") for (int k = 0; k < 2; ++k) dst[m][k] = *(const PG8_LAS bf16x8*)(lds + PG8_SA(b, h) + aoff + m * 2048 + k * 1024); } while (0)
; #define PG8_LDB(dst, b, h) do { _Pragma("unroll") for (int n = 0; n < 2; ++n) _Pragma("unroll") for (int k = 0; k < 2; ++k) dst[n][k] = *(const PG8_LAS bf16x8*)(lds + PG8_SB(b, h) + boff + n * 2048 + k * 1024); } while (0)
; #define PG8_MMA(ai, bj, At, Bt) do { __builtin_amdgcn_s_setprio(1); _Pragma("unroll") for (int m = 0; m < 4; ++m) _Pragma("unroll") for (int n = 0; n < 2; ++n) _Pragma("unroll") for (int k = 0; k < 2; ++k) \
;         acc[ai][bj][m][n] = __builtin_amdgcn_mfma_f32_16x16x32_bf16(Bt[n][k], At[m][k], acc[ai][bj][m][n], 0, 0, 0); __builtin_amdgcn_s_setprio(0); } while (0)
; #define PG8_BAR __builtin_amdgcn_s_barrier()
; template <class Epi, class Sched, bool ALIGN_EPI = false, bool SP2 = false>
; __device__ __forceinline__ void gemm_phase(PG8_LAS unsigned char* lds, const Gemm g, const Sched& S, const Epi& E, int wave_s) {
;     ...
;             PG8_LDB(B0, 0, 0); PG8_LDB(B1, 0, 1); PG8_SCHED; PG8_LDA(At, 0, 0); PG8_STAGE(PG8_SA(1, 1), a1 + hstepA, voffA);
;             PG8_WAIT_V(8); PG8_WAIT_L(0); PG8_BAR; PG8_MMA(0, 0, At, B0); PG8_MMA(0, 1, At, B1); PG8_BAR; PG8_SCHED;
;             PG8_LDA(At, 0, 1); PG8_STAGE(PG8_SB(0, 0), b2, voffB); PG8_STAGE(PG8_SB(0, 1), b2 + hstepB, voffB); PG8_STAGE(PG8_SA(0, 0), a2, voffA);
;             PG8_WAIT_V(8); PG8_WAIT_L(0); PG8_BAR; PG8_MMA(1, 0, At, B0); PG8_MMA(1, 1, At, B1); PG8_BAR; PG8_SCHED;
;             PG8_LDB(B0, 1, 0); PG8_LDB(B1, 1, 1); PG8_SCHED; PG8_LDA(At, 1, 0); PG8_STAGE(PG8_SA(0, 1), a2 + hstepA, voffA);
;             PG8_WAIT_V(8); PG8_WAIT_L(0); PG8_BAR; PG8_MMA(0, 0, At, B0); PG8_MMA(0, 1, At, B1); PG8_BAR; PG8_SCHED;
;             PG8_LDA(At, 1, 1); PG8_STAGE(PG8_SB(1, 0), b3, voffB); PG8_STAGE(PG8_SB(1, 1), b3 + hstepB, voffB); PG8_STAGE(PG8_SA(1, 0), a3, voffA);
;             PG8_WAIT_V(8); PG8_WAIT_L(0); PG8_BAR; PG8_MMA(1, 0, At, B0); PG8_MMA(1, 1, At, B1); PG8_BAR; PG8_SCHED;
	s_setprio 1
	s_waitcnt lgkmcnt(0)
	v_mfma_f32_16x16x32_bf16 v[64:67], v[146:149], v[194:197], v[64:67]
	v_mfma_f32_16x16x32_bf16 v[56:59], v[154:157], v[194:197], v[56:59]
	v_mfma_f32_16x16x32_bf16 v[48:51], v[146:149], v[212:215], v[48:51]
	v_mfma_f32_16x16x32_bf16 v[40:43], v[154:157], v[212:215], v[40:43]
	v_mfma_f32_16x16x32_bf16 v[32:35], v[146:149], v[220:223], v[32:35]
	v_mfma_f32_16x16x32_bf16 v[24:27], v[154:157], v[220:223], v[24:27]
	v_mfma_f32_16x16x32_bf16 v[16:19], v[146:149], v[228:231], v[16:19]
	v_mfma_f32_16x16x32_bf16 v[8:11], v[154:157], v[228:231], v[8:11]
	v_mfma_f32_16x16x32_bf16 v[64:67], v[150:153], v[198:201], v[64:67]
	v_mfma_f32_16x16x32_bf16 v[56:59], v[158:161], v[198:201], v[56:59]
	v_mfma_f32_16x16x32_bf16 v[48:51], v[150:153], v[216:219], v[48:51]
	v_mfma_f32_16x16x32_bf16 v[40:43], v[158:161], v[216:219], v[40:43]
	v_mfma_f32_16x16x32_bf16 v[32:35], v[150:153], v[224:227], v[32:35]
	v_mfma_f32_16x16x32_bf16 v[24:27], v[158:161], v[224:227], v[24:27]
	v_mfma_f32_16x16x32_bf16 v[16:19], v[150:153], v[232:235], v[16:19]
	v_mfma_f32_16x16x32_bf16 v[8:11], v[158:161], v[232:235], v[8:11]
	s_setprio 0
	s_setprio 1
	v_mfma_f32_16x16x32_bf16 v[60:63], v[162:165], v[194:197], v[60:63]
	v_mfma_f32_16x16x32_bf16 v[52:55], v[186:189], v[194:197], v[52:55]
	v_mfma_f32_16x16x32_bf16 v[44:47], v[162:165], v[212:215], v[44:47]
	v_mfma_f32_16x16x32_bf16 v[36:39], v[186:189], v[212:215], v[36:39]
	v_mfma_f32_16x16x32_bf16 v[28:31], v[162:165], v[220:223], v[28:31]
	v_mfma_f32_16x16x32_bf16 v[20:23], v[186:189], v[220:223], v[20:23]
	v_mfma_f32_16x16x32_bf16 v[12:15], v[162:165], v[228:231], v[12:15]
	v_mfma_f32_16x16x32_bf16 v[4:7], v[186:189], v[228:231], v[4:7]
	v_mfma_f32_16x16x32_bf16 v[60:63], v[182:185], v[198:201], v[60:63]
	v_mfma_f32_16x16x32_bf16 v[52:55], v[190:193], v[198:201], v[52:55]
	v_mfma_f32_16x16x32_bf16 v[44:47], v[182:185], v[216:219], v[44:47]
	v_mfma_f32_16x16x32_bf16 v[36:39], v[190:193], v[216:219], v[36:39]
	v_mfma_f32_16x16x32_bf16 v[28:31], v[182:185], v[224:227], v[28:31]
	v_mfma_f32_16x16x32_bf16 v[20:23], v[190:193], v[224:227], v[20:23]
	v_mfma_f32_16x16x32_bf16 v[12:15], v[182:185], v[232:235], v[12:15]
	v_mfma_f32_16x16x32_bf16 v[4:7], v[190:193], v[232:235], v[4:7]
	s_setprio 0
	s_barrier
	s_add_i32 s56, 0, 0x18000
	s_add_i32 s57, 0, 0x1c000
	v_add_u32_e32 v158, s56, v143
	v_add_u32_e32 v173, s57, v143
	ds_read_b128 v[146:149], v158
	ds_read_b128 v[150:153], v158 offset:1024
	ds_read_b128 v[154:157], v158 offset:2048
	ds_read_b128 v[158:161], v158 offset:3072
	ds_read_b128 v[162:165], v173
	ds_read_b128 v[182:185], v173 offset:1024
	ds_read_b128 v[186:189], v173 offset:2048
	ds_read_b128 v[190:193], v173 offset:3072
	s_add_u32 s38, s38, 0x80000
	s_addc_u32 s39, s39, 0
	s_mov_b32 m0, s45
	ds_read_b128 v[194:197], v145 offset:32768
	ds_read_b128 v[198:201], v145 offset:33792
	ds_read_b128 v[212:215], v145 offset:34816
	ds_read_b128 v[216:219], v145 offset:35840
	ds_read_b128 v[220:223], v145 offset:36864
	ds_read_b128 v[224:227], v145 offset:37888
	ds_read_b128 v[228:231], v145 offset:38912
	ds_read_b128 v[232:235], v145 offset:39936
	global_load_lds_dwordx4 v134, s[38:39]
	s_mov_b32 m0, s46
	s_nop 0
	global_load_lds_dwordx4 v132, s[38:39]
	s_waitcnt vmcnt(8)
	s_waitcnt lgkmcnt(0)
	s_barrier
	s_setprio 1
	s_waitcnt lgkmcnt(0)
	v_mfma_f32_16x16x32_bf16 v[128:131], v[146:149], v[194:197], v[128:131]
	v_mfma_f32_16x16x32_bf16 v[120:123], v[154:157], v[194:197], v[120:123]
	v_mfma_f32_16x16x32_bf16 v[112:115], v[146:149], v[212:215], v[112:115]
	v_mfma_f32_16x16x32_bf16 v[104:107], v[154:157], v[212:215], v[104:107]
	v_mfma_f32_16x16x32_bf16 v[96:99], v[146:149], v[220:223], v[96:99]
	v_mfma_f32_16x16x32_bf16 v[88:91], v[154:157], v[220:223], v[88:91]
	v_mfma_f32_16x16x32_bf16 v[80:83], v[146:149], v[228:231], v[80:83]
	v_mfma_f32_16x16x32_bf16 v[72:75], v[154:157], v[228:231], v[72:75]
	v_mfma_f32_16x16x32_bf16 v[128:131], v[150:153], v[198:201], v[128:131]
	v_mfma_f32_16x16x32_bf16 v[120:123], v[158:161], v[198:201], v[120:123]
	v_mfma_f32_16x16x32_bf16 v[112:115], v[150:153], v[216:219], v[112:115]
	v_mfma_f32_16x16x32_bf16 v[104:107], v[158:161], v[216:219], v[104:107]
	v_mfma_f32_16x16x32_bf16 v[96:99], v[150:153], v[224:227], v[96:99]
	v_mfma_f32_16x16x32_bf16 v[88:91], v[158:161], v[224:227], v[88:91]
	v_mfma_f32_16x16x32_bf16 v[80:83], v[150:153], v[232:235], v[80:83]
	v_mfma_f32_16x16x32_bf16 v[72:75], v[158:161], v[232:235], v[72:75]
	s_setprio 0
	s_setprio 1
	v_mfma_f32_16x16x32_bf16 v[124:127], v[162:165], v[194:197], v[124:127]
	v_mfma_f32_16x16x32_bf16 v[116:119], v[186:189], v[194:197], v[116:119]
	v_mfma_f32_16x16x32_bf16 v[108:111], v[162:165], v[212:215], v[108:111]
	v_mfma_f32_16x16x32_bf16 v[100:103], v[186:189], v[212:215], v[100:103]
	v_mfma_f32_16x16x32_bf16 v[92:95], v[162:165], v[220:223], v[92:95]
	v_mfma_f32_16x16x32_bf16 v[84:87], v[186:189], v[220:223], v[84:87]
	v_mfma_f32_16x16x32_bf16 v[76:79], v[162:165], v[228:231], v[76:79]
	v_mfma_f32_16x16x32_bf16 v[68:71], v[186:189], v[228:231], v[68:71]
	v_mfma_f32_16x16x32_bf16 v[124:127], v[182:185], v[198:201], v[124:127]
	v_mfma_f32_16x16x32_bf16 v[116:119], v[190:193], v[198:201], v[116:119]
	v_mfma_f32_16x16x32_bf16 v[108:111], v[182:185], v[216:219], v[108:111]
	v_mfma_f32_16x16x32_bf16 v[100:103], v[190:193], v[216:219], v[100:103]
	v_mfma_f32_16x16x32_bf16 v[92:95], v[182:185], v[224:227], v[92:95]
	v_mfma_f32_16x16x32_bf16 v[84:87], v[190:193], v[224:227], v[84:87]
	v_mfma_f32_16x16x32_bf16 v[76:79], v[182:185], v[232:235], v[76:79]
	v_mfma_f32_16x16x32_bf16 v[68:71], v[190:193], v[232:235], v[68:71]
	s_setprio 0
	s_barrier
; #define PG8_STAGE(bufoff, gbase, voff) do { _Pragma("unroll") for (int _i = 0; _i < 2; ++_i) \
;         __builtin_amdgcn_global_load_lds((const unsigned*)((const char*)(gbase) + (voff)[_i]), (PG8_LAS unsigned*)(lds + (bufoff) + ldsw + _i * 8192), 16, 0, 0); } while (0)
; #define PG8_LDA(dst, b, h) do { _Pragma("unroll") for (int m = 0; m < 4; ++m) _Pragma("unroll") for (int k = 0; k < 2; ++k) dst[m][k] = *(const PG8_LAS bf16x8*)(lds + PG8_SA(b, h) + aoff + m * 2048 + k * 1024); } while (0)
; #define PG8_WAIT_V(n) asm volatile("s_waitcnt vmcnt(" #n ")" ::: "memory")
; #define PG8_WAIT_L(n) asm volatile("s_waitcnt lgkmcnt(" #n ")" ::: "memory")
; #define PG8_BAR __builtin_amdgcn_s_barrier()
; template <class Epi, class Sched, bool ALIGN_EPI = false, bool SP2 = false>
; __device__ __forceinline__ void gemm_phase(PG8_LAS unsigned char* lds, const Gemm g, const Sched& S, const Epi& E, int wave_s) {
;     ...
;         for (int t = 0; t < nt; t += 2) {
;             const bool last = (t == nt - 2);
;             const char* a1 = cA + (size_t)(t + 1) * kstep;
;             const char* a2 = last ? nA : cA + (size_t)(t + 2) * kstep; const char* b2 = last ? nB : cB + (size_t)(t + 2) * kstep;
;             const char* a3 = a2 + kstep; const char* b3 = b2 + kstep;
;             if (last && has_next) S.a_ready(nxt);
;             if constexpr (SP2) {
;             PG8_LDB(B0, 0, 0); PG8_LDB(B1, 0, 1); PG8_SCHED; PG8_LDA(At, 0, 0); PG8_STAGE(PG8_SA(1, 1), a1 + hstepA, voffA);
;             PG8_WAIT_V(8); PG8_WAIT_L(0); PG8_BAR; PG8_MMA(0, 0, At, B0); PG8_MMA(0, 1, At, B1); PG8_BAR; PG8_SCHED;
;             PG8_LDA(At, 0, 1); PG8_STAGE(PG8_SB(0, 0), b2, voffB); PG8_STAGE(PG8_SB(0, 1), b2 + hstepB, voffB); PG8_STAGE(PG8_SA(0, 0), a2, voffA);
;             PG8_WAIT_V(8); PG8_WAIT_L(0); PG8_BAR; PG8_MMA(1, 0, At, B0); PG8_MMA(1, 1, At, B1); PG8_BAR; PG8_SCHED;
;             PG8_LDB(B0, 1, 0); PG8_LDB(B1, 1, 1); PG8_SCHED; PG8_LDA(At, 1, 0); PG8_STAGE(PG8_SA(0, 1), a2 + hstepA, voffA);
;             PG8_WAIT_V(8); PG8_WAIT_L(0); PG8_BAR; PG8_MMA(0, 0, At, B0); PG8_MMA(0, 1, At, B1); PG8_BAR; PG8_SCHED;
;             PG8_LDA(At, 1, 1); PG8_STAGE(PG8_SB(1, 0), b3, voffB); PG8_STAGE(PG8_SB(1, 1), b3 + hstepB, voffB); PG8_STAGE(PG8_SA(1, 0), a3, voffA);
;             PG8_WAIT_V(8); PG8_WAIT_L(0); PG8_BAR; PG8_MMA(1, 0, At, B0); PG8_MMA(1, 1, At, B1); PG8_BAR; PG8_SCHED;
	s_add_i32 s38, s56, s42
	s_mov_b32 m0, s38
	ds_read_b128 v[194:197], v145 offset:49152
	ds_read_b128 v[198:201], v145 offset:50176
	ds_read_b128 v[212:215], v145 offset:51200
	ds_read_b128 v[216:219], v145 offset:52224
	ds_read_b128 v[220:223], v145 offset:53248
	ds_read_b128 v[224:227], v145 offset:54272
	ds_read_b128 v[228:231], v145 offset:55296
	ds_read_b128 v[232:235], v145 offset:56320
	global_load_lds_dwordx4 v2, s[98:99]
	s_add_i32 m0, s38, 0x2000
	s_add_u32 s26, s26, 0x80080
	s_addc_u32 s27, s27, 0
	s_add_i32 s38, s57, s42
	global_load_lds_dwordx4 v0, s[98:99]
	s_mov_b32 m0, s38
	s_nop 0
	global_load_lds_dwordx4 v2, s[26:27]
	s_add_i32 m0, s38, 0x2000
	s_nop 0
	global_load_lds_dwordx4 v0, s[26:27]
	s_mov_b32 m0, s47
	s_nop 0
	global_load_lds_dwordx4 v134, s[100:101]
	s_mov_b32 m0, s48
	s_nop 0
	global_load_lds_dwordx4 v132, s[100:101]
	s_waitcnt vmcnt(8)
	s_waitcnt lgkmcnt(0)
	s_barrier
	s_setprio 1
	s_waitcnt lgkmcnt(0)
	v_mfma_f32_16x16x32_bf16 v[64:67], v[146:149], v[194:197], v[64:67]
	v_mfma_f32_16x16x32_bf16 v[56:59], v[154:157], v[194:197], v[56:59]
	v_mfma_f32_16x16x32_bf16 v[48:51], v[146:149], v[212:215], v[48:51]
	v_mfma_f32_16x16x32_bf16 v[40:43], v[154:157], v[212:215], v[40:43]
	v_mfma_f32_16x16x32_bf16 v[32:35], v[146:149], v[220:223], v[32:35]
	v_mfma_f32_16x16x32_bf16 v[24:27], v[154:157], v[220:223], v[24:27]
	v_mfma_f32_16x16x32_bf16 v[16:19], v[146:149], v[228:231], v[16:19]
	v_mfma_f32_16x16x32_bf16 v[8:11], v[154:157], v[228:231], v[8:11]
	v_mfma_f32_16x16x32_bf16 v[64:67], v[150:153], v[198:201], v[64:67]
	v_mfma_f32_16x16x32_bf16 v[56:59], v[158:161], v[198:201], v[56:59]
	v_mfma_f32_16x16x32_bf16 v[48:51], v[150:153], v[216:219], v[48:51]
	v_mfma_f32_16x16x32_bf16 v[40:43], v[158:161], v[216:219], v[40:43]
	v_mfma_f32_16x16x32_bf16 v[32:35], v[150:153], v[224:227], v[32:35]
	v_mfma_f32_16x16x32_bf16 v[24:27], v[158:161], v[224:227], v[24:27]
	v_mfma_f32_16x16x32_bf16 v[16:19], v[150:153], v[232:235], v[16:19]
	v_mfma_f32_16x16x32_bf16 v[8:11], v[158:161], v[232:235], v[8:11]
	s_setprio 0
	s_setprio 1
	v_mfma_f32_16x16x32_bf16 v[60:63], v[162:165], v[194:197], v[60:63]
	v_mfma_f32_16x16x32_bf16 v[52:55], v[186:189], v[194:197], v[52:55]
	v_mfma_f32_16x16x32_bf16 v[44:47], v[162:165], v[212:215], v[44:47]
	v_mfma_f32_16x16x32_bf16 v[36:39], v[186:189], v[212:215], v[36:39]
	v_mfma_f32_16x16x32_bf16 v[28:31], v[162:165], v[220:223], v[28:31]
	v_mfma_f32_16x16x32_bf16 v[20:23], v[186:189], v[220:223], v[20:23]
	v_mfma_f32_16x16x32_bf16 v[12:15], v[162:165], v[228:231], v[12:15]
	v_mfma_f32_16x16x32_bf16 v[4:7], v[186:189], v[228:231], v[4:7]
	v_mfma_f32_16x16x32_bf16 v[60:63], v[182:185], v[198:201], v[60:63]
	v_mfma_f32_16x16x32_bf16 v[52:55], v[190:193], v[198:201], v[52:55]
	v_mfma_f32_16x16x32_bf16 v[44:47], v[182:185], v[216:219], v[44:47]
	v_mfma_f32_16x16x32_bf16 v[36:39], v[190:193], v[216:219], v[36:39]
	v_mfma_f32_16x16x32_bf16 v[28:31], v[182:185], v[224:227], v[28:31]
	v_mfma_f32_16x16x32_bf16 v[20:23], v[190:193], v[224:227], v[20:23]
	v_mfma_f32_16x16x32_bf16 v[12:15], v[182:185], v[232:235], v[12:15]
	v_mfma_f32_16x16x32_bf16 v[4:7], v[190:193], v[232:235], v[4:7]
	s_setprio 0
	s_barrier
	s_add_i32 s55, s55, 2
	s_add_u32 s53, s53, 0x100
	s_addc_u32 s54, s54, 0
	s_add_u32 s18, s18, 0x100
	s_addc_u32 s19, s19, 0
	s_cmp_gt_u32 s55, 29
	s_cbranch_scc0 .LBB0_790
	s_and_b64 vcc, exec, s[6:7]
	s_cbranch_vccz .LBB0_793
	s_barrier

; #define PG8_STAGE(bufoff, gbase, voff) do { _Pragma("unroll") for (int _i = 0; _i < 2; ++_i) \
;         __builtin_amdgcn_global_load_lds((const unsigned*)((const char*)(gbase) + (voff)[_i]), (PG8_LAS unsigned*)(lds + (bufoff) + ldsw + _i * 8192), 16, 0, 0); } while (0)
; #define PG8_LDA(dst, b, h) do { _Pragma("unroll") for (int m = 0; m < 4; ++m) _Pragma("unroll") for (int k = 0; k < 2; ++k) dst[m][k] = *(const PG8_LAS bf16x8*)(lds + PG8_SA(b, h) + aoff + m * 2048 + k * 1024); } while (0)
; #define PG8_LDB(dst, b, h) do { _Pragma("unroll") for (int n = 0; n < 2; ++n) _Pragma("unroll") for (int k = 0; k < 2; ++k) dst[n][k] = *(const PG8_LAS bf16x8*)(lds + PG8_SB(b, h) + boff + n * 2048 + k * 1024); } while (0)
; template <class Epi, class Sched, bool ALIGN_EPI = false, bool SP2 = false>
; __device__ __forceinline__ void gemm_phase(PG8_LAS unsigned char* lds, const Gemm g, const Sched& S, const Epi& E, int wave_s) {
;     ...
;             const bool last = (t == nt - 2);
;             const char* a1 = cA + (size_t)(t + 1) * kstep;
;             const char* a2 = last ? nA : cA + (size_t)(t + 2) * kstep; const char* b2 = last ? nB : cB + (size_t)(t + 2) * kstep;
;             const char* a3 = a2 + kstep; const char* b3 = b2 + kstep;
;             if (last && has_next) S.a_ready(nxt);
;             if constexpr (SP2) {
;             PG8_LDB(B0, 0, 0); PG8_LDB(B1, 0, 1); PG8_SCHED; PG8_LDA(At, 0, 0); PG8_STAGE(PG8_SA(1, 1), a1 + hstepA, voffA);
;             PG8_WAIT_V(8); PG8_WAIT_L(0); PG8_BAR; PG8_MMA(0, 0, At, B0); PG8_MMA(0, 1, At, B1); PG8_BAR; PG8_SCHED;
;             PG8_LDA(At, 0, 1); PG8_STAGE(PG8_SB(0, 0), b2, voffB); PG8_STAGE(PG8_SB(0, 1), b2 + hstepB, voffB); PG8_STAGE(PG8_SA(0, 0), a2, voffA);
;             PG8_WAIT_V(8); PG8_WAIT_L(0); PG8_BAR; PG8_MMA(1, 0, At, B0); PG8_MMA(1, 1, At, B1); PG8_BAR; PG8_SCHED;
;             PG8_LDB(B0, 1, 0); PG8_LDB(B1, 1, 1); PG8_SCHED; PG8_LDA(At, 1, 0); PG8_STAGE(PG8_SA(0, 1), a2 + hstepA, voffA);
;             PG8_WAIT_V(8); PG8_WAIT_L(0); PG8_BAR; PG8_MMA(0, 0, At, B0); PG8_MMA(0, 1, At, B1); PG8_BAR; PG8_SCHED;
;             PG8_LDA(At, 1, 1); PG8_STAGE(PG8_SB(1, 0), b3, voffB); PG8_STAGE(PG8_SB(1, 1), b3 + hstepB, voffB); PG8_STAGE(PG8_SA(1, 0), a3, voffA);
;             PG8_WAIT_V(8); PG8_WAIT_L(0); PG8_BAR; PG8_MMA(1, 0, At, B0); PG8_MMA(1, 1, At, B1); PG8_BAR; PG8_SCHED;
.LBB0_863:
	s_add_u32 s22, s20, 0x100
	s_addc_u32 s23, s21, 0
	s_add_i32 s54, 0, 0x10000
	s_cmpk_eq_i32 s53, 0x54
	s_cselect_b32 s27, s17, s23
	s_cselect_b32 s26, s16, s22
	s_cselect_b32 s25, s19, s37
	s_cselect_b32 s24, s18, s36
	s_add_i32 s55, 0, 0x14000
	v_add_u32_e32 v144, s54, v184
	v_add_u32_e32 v182, s55, v184
	ds_read_b128 v[132:135], v144
	ds_read_b128 v[136:139], v144 offset:1024
	ds_read_b128 v[140:143], v144 offset:2048
	ds_read_b128 v[144:147], v144 offset:3072
	ds_read_b128 v[148:151], v182
	ds_read_b128 v[160:163], v182 offset:1024
	ds_read_b128 v[164:167], v182 offset:2048
	ds_read_b128 v[188:191], v182 offset:3072
	v_lshl_add_u64 v[182:183], s[20:21], 0, v[158:159]
	s_add_i32 m0, s41, 0xc000
	ds_read_b128 v[192:195], v186
	ds_read_b128 v[196:199], v186 offset:1024
	ds_read_b128 v[212:215], v186 offset:2048
	ds_read_b128 v[216:219], v186 offset:3072
	ds_read_b128 v[220:223], v186 offset:4096
	ds_read_b128 v[224:227], v186 offset:5120
	ds_read_b128 v[228:231], v186 offset:6144
	ds_read_b128 v[232:235], v186 offset:7168
	global_load_lds_dwordx4 v[182:183], off
	v_lshl_add_u64 v[182:183], s[20:21], 0, v[156:157]
	s_add_i32 m0, s41, 0xe000
	s_nop 0
	global_load_lds_dwordx4 v[182:183], off
	s_waitcnt vmcnt(8)
	s_waitcnt lgkmcnt(0)
	s_barrier
	s_setprio 1
	s_waitcnt lgkmcnt(0)
	v_mfma_f32_16x16x32_bf16 v[128:131], v[132:135], v[192:195], v[128:131]
	v_mfma_f32_16x16x32_bf16 v[124:127], v[140:143], v[192:195], v[124:127]
	v_mfma_f32_16x16x32_bf16 v[120:123], v[132:135], v[212:215], v[120:123]
	v_mfma_f32_16x16x32_bf16 v[116:119], v[140:143], v[212:215], v[116:119]
	v_mfma_f32_16x16x32_bf16 v[96:99], v[132:135], v[220:223], v[96:99]
	v_mfma_f32_16x16x32_bf16 v[92:95], v[140:143], v[220:223], v[92:95]
	v_mfma_f32_16x16x32_bf16 v[80:83], v[132:135], v[228:231], v[80:83]
	v_mfma_f32_16x16x32_bf16 v[76:79], v[140:143], v[228:231], v[76:79]
	v_mfma_f32_16x16x32_bf16 v[128:131], v[136:139], v[196:199], v[128:131]
	v_mfma_f32_16x16x32_bf16 v[124:127], v[144:147], v[196:199], v[124:127]
	v_mfma_f32_16x16x32_bf16 v[120:123], v[136:139], v[216:219], v[120:123]
	v_mfma_f32_16x16x32_bf16 v[116:119], v[144:147], v[216:219], v[116:119]
	v_mfma_f32_16x16x32_bf16 v[96:99], v[136:139], v[224:227], v[96:99]
	v_mfma_f32_16x16x32_bf16 v[92:95], v[144:147], v[224:227], v[92:95]
	v_mfma_f32_16x16x32_bf16 v[80:83], v[136:139], v[232:235], v[80:83]
	v_mfma_f32_16x16x32_bf16 v[76:79], v[144:147], v[232:235], v[76:79]
	s_setprio 0
	s_setprio 1
	v_mfma_f32_16x16x32_bf16 v[112:115], v[148:151], v[192:195], v[112:115]
	v_mfma_f32_16x16x32_bf16 v[108:111], v[164:167], v[192:195], v[108:111]
	v_mfma_f32_16x16x32_bf16 v[104:107], v[148:151], v[212:215], v[104:107]
	v_mfma_f32_16x16x32_bf16 v[100:103], v[164:167], v[212:215], v[100:103]
	v_mfma_f32_16x16x32_bf16 v[88:91], v[148:151], v[220:223], v[88:91]
	v_mfma_f32_16x16x32_bf16 v[84:87], v[164:167], v[220:223], v[84:87]
	v_mfma_f32_16x16x32_bf16 v[72:75], v[148:151], v[228:231], v[72:75]
	v_mfma_f32_16x16x32_bf16 v[68:71], v[164:167], v[228:231], v[68:71]
	v_mfma_f32_16x16x32_bf16 v[112:115], v[160:163], v[196:199], v[112:115]
	v_mfma_f32_16x16x32_bf16 v[108:111], v[188:191], v[196:199], v[108:111]
	v_mfma_f32_16x16x32_bf16 v[104:107], v[160:163], v[216:219], v[104:107]
	v_mfma_f32_16x16x32_bf16 v[100:103], v[188:191], v[216:219], v[100:103]
	v_mfma_f32_16x16x32_bf16 v[88:91], v[160:163], v[224:227], v[88:91]
	v_mfma_f32_16x16x32_bf16 v[84:87], v[188:191], v[224:227], v[84:87]
	v_mfma_f32_16x16x32_bf16 v[72:75], v[160:163], v[232:235], v[72:75]
	v_mfma_f32_16x16x32_bf16 v[68:71], v[188:191], v[232:235], v[68:71]
	s_setprio 0
	s_barrier
	s_add_i32 s20, s54, s40
	s_add_u32 s98, s24, s60
	s_addc_u32 s99, s25, s61
	s_mov_b32 m0, s20
	ds_read_b128 v[192:195], v186 offset:16384
	ds_read_b128 v[196:199], v186 offset:17408
	ds_read_b128 v[212:215], v186 offset:18432
	ds_read_b128 v[216:219], v186 offset:19456
	ds_read_b128 v[220:223], v186 offset:20480
	ds_read_b128 v[224:227], v186 offset:21504
	ds_read_b128 v[228:231], v186 offset:22528
	ds_read_b128 v[232:235], v186 offset:23552
	global_load_lds_dwordx4 v2, s[24:25]
	s_add_i32 m0, s20, 0x2000
	s_add_u32 s20, s24, 0x160000
	s_addc_u32 s21, s25, 0
	s_add_i32 s54, s55, s40
	global_load_lds_dwordx4 v0, s[24:25]
	s_mov_b32 m0, s54
	s_add_u32 s100, s26, s60
	s_addc_u32 s101, s27, s61
	s_nop 0
	global_load_lds_dwordx4 v2, s[20:21]
	s_add_i32 m0, s54, 0x2000
	s_nop 0
	global_load_lds_dwordx4 v0, s[20:21]
	s_mov_b32 m0, s41
	s_nop 0
	global_load_lds_dwordx4 v154, s[26:27]
	s_mov_b32 m0, s42
	s_nop 0
	global_load_lds_dwordx4 v152, s[26:27]
	s_waitcnt vmcnt(8)
	s_waitcnt lgkmcnt(0)
	s_barrier
; #define PG8_STAGE(bufoff, gbase, voff) do { _Pragma("unroll") for (int _i = 0; _i < 2; ++_i) \
;         __builtin_amdgcn_global_load_lds((const unsigned*)((const char*)(gbase) + (voff)[_i]), (PG8_LAS unsigned*)(lds + (bufoff) + ldsw + _i * 8192), 16, 0, 0); } while (0)
; #define PG8_LDA(dst, b, h) do { _Pragma("unroll") for (int m = 0; m < 4; ++m) _Pragma("unroll") for (int k = 0; k < 2; ++k) dst[m][k] = *(const PG8_LAS bf16x8*)(lds + PG8_SA(b, h) + aoff + m * 2048 + k * 1024); } while (0)
; #define PG8_LDB(dst, b, h) do { _Pragma("unroll") for (int n = 0; n < 2; ++n) _Pragma("unroll") for (int k = 0; k < 2; ++k) dst[n][k] = *(const PG8_LAS bf16x8*)(lds + PG8_SB(b, h) + boff + n * 2048 + k * 1024); } while (0)
; #define PG8_MMA(ai, bj, At, Bt) do { __builtin_amdgcn_s_setprio(1); _Pragma("unroll") for (int m = 0; m < 4; ++m) _Pragma("unroll") for (int n = 0; n < 2; ++n) _Pragma("unroll") for (int k = 0; k < 2; ++k) \
;         acc[ai][bj][m][n] = __builtin_amdgcn_mfma_f32_16x16x32_bf16(Bt[n][k], At[m][k], acc[ai][bj][m][n], 0, 0, 0); __builtin_amdgcn_s_setprio(0); } while (0)
; #define PG8_BAR __builtin_amdgcn_s_barrier()
; template <class Epi, class Sched, bool ALIGN_EPI = false, bool SP2 = false>
; __device__ __forceinline__ void gemm_phase(PG8_LAS unsigned char* lds, const Gemm g, const Sched& S, const Epi& E, int wave_s) {
;     ...
;             PG8_LDB(B0, 0, 0); PG8_LDB(B1, 0, 1); PG8_SCHED; PG8_LDA(At, 0, 0); PG8_STAGE(PG8_SA(1, 1), a1 + hstepA, voffA);
;             PG8_WAIT_V(8); PG8_WAIT_L(0); PG8_BAR; PG8_MMA(0, 0, At, B0); PG8_MMA(0, 1, At, B1); PG8_BAR; PG8_SCHED;
;             PG8_LDA(At, 0, 1); PG8_STAGE(PG8_SB(0, 0), b2, voffB); PG8_STAGE(PG8_SB(0, 1), b2 + hstepB, voffB); PG8_STAGE(PG8_SA(0, 0), a2, voffA);
;             PG8_WAIT_V(8); PG8_WAIT_L(0); PG8_BAR; PG8_MMA(1, 0, At, B0); PG8_MMA(1, 1, At, B1); PG8_BAR; PG8_SCHED;
;             PG8_LDB(B0, 1, 0); PG8_LDB(B1, 1, 1); PG8_SCHED; PG8_LDA(At, 1, 0); PG8_STAGE(PG8_SA(0, 1), a2 + hstepA, voffA);
;             PG8_WAIT_V(8); PG8_WAIT_L(0); PG8_BAR; PG8_MMA(0, 0, At, B0); PG8_MMA(0, 1, At, B1); PG8_BAR; PG8_SCHED;
;             PG8_LDA(At, 1, 1); PG8_STAGE(PG8_SB(1, 0), b3, voffB); PG8_STAGE(PG8_SB(1, 1), b3 + hstepB, voffB); PG8_STAGE(PG8_SA(1, 0), a3, voffA);
;             PG8_WAIT_V(8); PG8_WAIT_L(0); PG8_BAR; PG8_MMA(1, 0, At, B0); PG8_MMA(1, 1, At, B1); PG8_BAR; PG8_SCHED;
	s_setprio 1
	s_waitcnt lgkmcnt(0)
	v_mfma_f32_16x16x32_bf16 v[64:67], v[132:135], v[192:195], v[64:67]
	v_mfma_f32_16x16x32_bf16 v[60:63], v[140:143], v[192:195], v[60:63]
	v_mfma_f32_16x16x32_bf16 v[48:51], v[132:135], v[212:215], v[48:51]
	v_mfma_f32_16x16x32_bf16 v[44:47], v[140:143], v[212:215], v[44:47]
	v_mfma_f32_16x16x32_bf16 v[32:35], v[132:135], v[220:223], v[32:35]
	v_mfma_f32_16x16x32_bf16 v[28:31], v[140:143], v[220:223], v[28:31]
	v_mfma_f32_16x16x32_bf16 v[16:19], v[132:135], v[228:231], v[16:19]
	v_mfma_f32_16x16x32_bf16 v[12:15], v[140:143], v[228:231], v[12:15]
	v_mfma_f32_16x16x32_bf16 v[64:67], v[136:139], v[196:199], v[64:67]
	v_mfma_f32_16x16x32_bf16 v[60:63], v[144:147], v[196:199], v[60:63]
	v_mfma_f32_16x16x32_bf16 v[48:51], v[136:139], v[216:219], v[48:51]
	v_mfma_f32_16x16x32_bf16 v[44:47], v[144:147], v[216:219], v[44:47]
	v_mfma_f32_16x16x32_bf16 v[32:35], v[136:139], v[224:227], v[32:35]
	v_mfma_f32_16x16x32_bf16 v[28:31], v[144:147], v[224:227], v[28:31]
	v_mfma_f32_16x16x32_bf16 v[16:19], v[136:139], v[232:235], v[16:19]
	v_mfma_f32_16x16x32_bf16 v[12:15], v[144:147], v[232:235], v[12:15]
	s_setprio 0
	s_setprio 1
	v_mfma_f32_16x16x32_bf16 v[56:59], v[148:151], v[192:195], v[56:59]
	v_mfma_f32_16x16x32_bf16 v[52:55], v[164:167], v[192:195], v[52:55]
	v_mfma_f32_16x16x32_bf16 v[40:43], v[148:151], v[212:215], v[40:43]
	v_mfma_f32_16x16x32_bf16 v[36:39], v[164:167], v[212:215], v[36:39]
	v_mfma_f32_16x16x32_bf16 v[24:27], v[148:151], v[220:223], v[24:27]
	v_mfma_f32_16x16x32_bf16 v[20:23], v[164:167], v[220:223], v[20:23]
	v_mfma_f32_16x16x32_bf16 v[8:11], v[148:151], v[228:231], v[8:11]
	v_mfma_f32_16x16x32_bf16 v[4:7], v[164:167], v[228:231], v[4:7]
	v_mfma_f32_16x16x32_bf16 v[56:59], v[160:163], v[196:199], v[56:59]
	v_mfma_f32_16x16x32_bf16 v[52:55], v[188:191], v[196:199], v[52:55]
	v_mfma_f32_16x16x32_bf16 v[40:43], v[160:163], v[216:219], v[40:43]
	v_mfma_f32_16x16x32_bf16 v[36:39], v[188:191], v[216:219], v[36:39]
	v_mfma_f32_16x16x32_bf16 v[24:27], v[160:163], v[224:227], v[24:27]
	v_mfma_f32_16x16x32_bf16 v[20:23], v[188:191], v[224:227], v[20:23]
	v_mfma_f32_16x16x32_bf16 v[8:11], v[160:163], v[232:235], v[8:11]
	v_mfma_f32_16x16x32_bf16 v[4:7], v[188:191], v[232:235], v[4:7]
	s_setprio 0
	s_barrier
	s_add_i32 s54, 0, 0x18000
	s_add_i32 s55, 0, 0x1c000
	v_add_u32_e32 v144, s54, v184
	v_add_u32_e32 v187, s55, v184
	ds_read_b128 v[132:135], v144
	ds_read_b128 v[136:139], v144 offset:1024
	ds_read_b128 v[140:143], v144 offset:2048
	ds_read_b128 v[144:147], v144 offset:3072
	ds_read_b128 v[148:151], v187
	ds_read_b128 v[160:163], v187 offset:1024
	ds_read_b128 v[164:167], v187 offset:2048
	ds_read_b128 v[188:191], v187 offset:3072
	s_add_u32 s20, s26, 0x160000
	s_addc_u32 s21, s27, 0
	s_mov_b32 m0, s43
	ds_read_b128 v[192:195], v186 offset:32768
	ds_read_b128 v[196:199], v186 offset:33792
	ds_read_b128 v[212:215], v186 offset:34816
	ds_read_b128 v[216:219], v186 offset:35840
	ds_read_b128 v[220:223], v186 offset:36864
	ds_read_b128 v[224:227], v186 offset:37888
	ds_read_b128 v[228:231], v186 offset:38912
	ds_read_b128 v[232:235], v186 offset:39936
	global_load_lds_dwordx4 v154, s[20:21]
	s_mov_b32 m0, s44
	s_nop 0
	global_load_lds_dwordx4 v152, s[20:21]
	s_waitcnt vmcnt(8)
	s_waitcnt lgkmcnt(0)
	s_barrier
	s_setprio 1
	s_waitcnt lgkmcnt(0)
	v_mfma_f32_16x16x32_bf16 v[128:131], v[132:135], v[192:195], v[128:131]
	v_mfma_f32_16x16x32_bf16 v[124:127], v[140:143], v[192:195], v[124:127]
	v_mfma_f32_16x16x32_bf16 v[120:123], v[132:135], v[212:215], v[120:123]
	v_mfma_f32_16x16x32_bf16 v[116:119], v[140:143], v[212:215], v[116:119]
	v_mfma_f32_16x16x32_bf16 v[96:99], v[132:135], v[220:223], v[96:99]
	v_mfma_f32_16x16x32_bf16 v[92:95], v[140:143], v[220:223], v[92:95]
	v_mfma_f32_16x16x32_bf16 v[80:83], v[132:135], v[228:231], v[80:83]
	v_mfma_f32_16x16x32_bf16 v[76:79], v[140:143], v[228:231], v[76:79]
	v_mfma_f32_16x16x32_bf16 v[128:131], v[136:139], v[196:199], v[128:131]
	v_mfma_f32_16x16x32_bf16 v[124:127], v[144:147], v[196:199], v[124:127]
	v_mfma_f32_16x16x32_bf16 v[120:123], v[136:139], v[216:219], v[120:123]
	v_mfma_f32_16x16x32_bf16 v[116:119], v[144:147], v[216:219], v[116:119]
	v_mfma_f32_16x16x32_bf16 v[96:99], v[136:139], v[224:227], v[96:99]
	v_mfma_f32_16x16x32_bf16 v[92:95], v[144:147], v[224:227], v[92:95]
	v_mfma_f32_16x16x32_bf16 v[80:83], v[136:139], v[232:235], v[80:83]
	v_mfma_f32_16x16x32_bf16 v[76:79], v[144:147], v[232:235], v[76:79]
	s_setprio 0
	s_setprio 1
	v_mfma_f32_16x16x32_bf16 v[112:115], v[148:151], v[192:195], v[112:115]
	v_mfma_f32_16x16x32_bf16 v[108:111], v[164:167], v[192:195], v[108:111]
	v_mfma_f32_16x16x32_bf16 v[104:107], v[148:151], v[212:215], v[104:107]
	v_mfma_f32_16x16x32_bf16 v[100:103], v[164:167], v[212:215], v[100:103]
	v_mfma_f32_16x16x32_bf16 v[88:91], v[148:151], v[220:223], v[88:91]
	v_mfma_f32_16x16x32_bf16 v[84:87], v[164:167], v[220:223], v[84:87]
	v_mfma_f32_16x16x32_bf16 v[72:75], v[148:151], v[228:231], v[72:75]
	v_mfma_f32_16x16x32_bf16 v[68:71], v[164:167], v[228:231], v[68:71]
	v_mfma_f32_16x16x32_bf16 v[112:115], v[160:163], v[196:199], v[112:115]
	v_mfma_f32_16x16x32_bf16 v[108:111], v[188:191], v[196:199], v[108:111]
	v_mfma_f32_16x16x32_bf16 v[104:107], v[160:163], v[216:219], v[104:107]
	v_mfma_f32_16x16x32_bf16 v[100:103], v[188:191], v[216:219], v[100:103]
	v_mfma_f32_16x16x32_bf16 v[88:91], v[160:163], v[224:227], v[88:91]
	v_mfma_f32_16x16x32_bf16 v[84:87], v[188:191], v[224:227], v[84:87]
	v_mfma_f32_16x16x32_bf16 v[72:75], v[160:163], v[232:235], v[72:75]
	v_mfma_f32_16x16x32_bf16 v[68:71], v[188:191], v[232:235], v[68:71]
	s_setprio 0
	s_barrier
; #define PG8_STAGE(bufoff, gbase, voff) do { _Pragma("unroll") for (int _i = 0; _i < 2; ++_i) \
;         __builtin_amdgcn_global_load_lds((const unsigned*)((const char*)(gbase) + (voff)[_i]), (PG8_LAS unsigned*)(lds + (bufoff) + ldsw + _i * 8192), 16, 0, 0); } while (0)
; #define PG8_LDA(dst, b, h) do { _Pragma("unroll") for (int m = 0; m < 4; ++m) _Pragma("unroll") for (int k = 0; k < 2; ++k) dst[m][k] = *(const PG8_LAS bf16x8*)(lds + PG8_SA(b, h) + aoff + m * 2048 + k * 1024); } while (0)
; #define PG8_WAIT_V(n) asm volatile("s_waitcnt vmcnt(" #n ")" ::: "memory")
; #define PG8_WAIT_L(n) asm volatile("s_waitcnt lgkmcnt(" #n ")" ::: "memory")
; #define PG8_BAR __builtin_amdgcn_s_barrier()
; template <class Epi, class Sched, bool ALIGN_EPI = false, bool SP2 = false>
; __device__ __forceinline__ void gemm_phase(PG8_LAS unsigned char* lds, const Gemm g, const Sched& S, const Epi& E, int wave_s) {
;     ...
;         for (int t = 0; t < nt; t += 2) {
;             const bool last = (t == nt - 2);
;             const char* a1 = cA + (size_t)(t + 1) * kstep;
;             const char* a2 = last ? nA : cA + (size_t)(t + 2) * kstep; const char* b2 = last ? nB : cB + (size_t)(t + 2) * kstep;
;             const char* a3 = a2 + kstep; const char* b3 = b2 + kstep;
;             if (last && has_next) S.a_ready(nxt);
;             if constexpr (SP2) {
;             PG8_LDB(B0, 0, 0); PG8_LDB(B1, 0, 1); PG8_SCHED; PG8_LDA(At, 0, 0); PG8_STAGE(PG8_SA(1, 1), a1 + hstepA, voffA);
;             PG8_WAIT_V(8); PG8_WAIT_L(0); PG8_BAR; PG8_MMA(0, 0, At, B0); PG8_MMA(0, 1, At, B1); PG8_BAR; PG8_SCHED;
;             PG8_LDA(At, 0, 1); PG8_STAGE(PG8_SB(0, 0), b2, voffB); PG8_STAGE(PG8_SB(0, 1), b2 + hstepB, voffB); PG8_STAGE(PG8_SA(0, 0), a2, voffA);
;             PG8_WAIT_V(8); PG8_WAIT_L(0); PG8_BAR; PG8_MMA(1, 0, At, B0); PG8_MMA(1, 1, At, B1); PG8_BAR; PG8_SCHED;
;             PG8_LDB(B0, 1, 0); PG8_LDB(B1, 1, 1); PG8_SCHED; PG8_LDA(At, 1, 0); PG8_STAGE(PG8_SA(0, 1), a2 + hstepA, voffA);
;             PG8_WAIT_V(8); PG8_WAIT_L(0); PG8_BAR; PG8_MMA(0, 0, At, B0); PG8_MMA(0, 1, At, B1); PG8_BAR; PG8_SCHED;
;             PG8_LDA(At, 1, 1); PG8_STAGE(PG8_SB(1, 0), b3, voffB); PG8_STAGE(PG8_SB(1, 1), b3 + hstepB, voffB); PG8_STAGE(PG8_SA(1, 0), a3, voffA);
;             PG8_WAIT_V(8); PG8_WAIT_L(0); PG8_BAR; PG8_MMA(1, 0, At, B0); PG8_MMA(1, 1, At, B1); PG8_BAR; PG8_SCHED;
	s_add_i32 s20, s54, s40
	s_mov_b32 m0, s20
	ds_read_b128 v[192:195], v186 offset:49152
	ds_read_b128 v[196:199], v186 offset:50176
	ds_read_b128 v[212:215], v186 offset:51200
	ds_read_b128 v[216:219], v186 offset:52224
	ds_read_b128 v[220:223], v186 offset:53248
	ds_read_b128 v[224:227], v186 offset:54272
	ds_read_b128 v[228:231], v186 offset:55296
	ds_read_b128 v[232:235], v186 offset:56320
	global_load_lds_dwordx4 v2, s[98:99]
	s_add_i32 m0, s20, 0x2000
	s_add_u32 s20, s24, 0x160080
	s_addc_u32 s21, s25, 0
	s_add_i32 s24, s55, s40
	global_load_lds_dwordx4 v0, s[98:99]
	s_mov_b32 m0, s24
	s_nop 0
	global_load_lds_dwordx4 v2, s[20:21]
	s_add_i32 m0, s24, 0x2000
	s_nop 0
	global_load_lds_dwordx4 v0, s[20:21]
	s_mov_b32 m0, s47
	s_nop 0
	global_load_lds_dwordx4 v154, s[100:101]
	s_mov_b32 m0, s48
	s_nop 0
	global_load_lds_dwordx4 v152, s[100:101]
	s_waitcnt vmcnt(8)
	s_waitcnt lgkmcnt(0)
	s_barrier
	s_setprio 1
	s_waitcnt lgkmcnt(0)
	v_mfma_f32_16x16x32_bf16 v[64:67], v[132:135], v[192:195], v[64:67]
	v_mfma_f32_16x16x32_bf16 v[60:63], v[140:143], v[192:195], v[60:63]
	v_mfma_f32_16x16x32_bf16 v[48:51], v[132:135], v[212:215], v[48:51]
	v_mfma_f32_16x16x32_bf16 v[44:47], v[140:143], v[212:215], v[44:47]
	v_mfma_f32_16x16x32_bf16 v[32:35], v[132:135], v[220:223], v[32:35]
	v_mfma_f32_16x16x32_bf16 v[28:31], v[140:143], v[220:223], v[28:31]
	v_mfma_f32_16x16x32_bf16 v[16:19], v[132:135], v[228:231], v[16:19]
	v_mfma_f32_16x16x32_bf16 v[12:15], v[140:143], v[228:231], v[12:15]
	v_mfma_f32_16x16x32_bf16 v[64:67], v[136:139], v[196:199], v[64:67]
	v_mfma_f32_16x16x32_bf16 v[60:63], v[144:147], v[196:199], v[60:63]
	v_mfma_f32_16x16x32_bf16 v[48:51], v[136:139], v[216:219], v[48:51]
	v_mfma_f32_16x16x32_bf16 v[44:47], v[144:147], v[216:219], v[44:47]
	v_mfma_f32_16x16x32_bf16 v[32:35], v[136:139], v[224:227], v[32:35]
	v_mfma_f32_16x16x32_bf16 v[28:31], v[144:147], v[224:227], v[28:31]
	v_mfma_f32_16x16x32_bf16 v[16:19], v[136:139], v[232:235], v[16:19]
	v_mfma_f32_16x16x32_bf16 v[12:15], v[144:147], v[232:235], v[12:15]
	s_setprio 0
	s_setprio 1
	v_mfma_f32_16x16x32_bf16 v[56:59], v[148:151], v[192:195], v[56:59]
	v_mfma_f32_16x16x32_bf16 v[52:55], v[164:167], v[192:195], v[52:55]
	v_mfma_f32_16x16x32_bf16 v[40:43], v[148:151], v[212:215], v[40:43]
	v_mfma_f32_16x16x32_bf16 v[36:39], v[164:167], v[212:215], v[36:39]
	v_mfma_f32_16x16x32_bf16 v[24:27], v[148:151], v[220:223], v[24:27]
	v_mfma_f32_16x16x32_bf16 v[20:23], v[164:167], v[220:223], v[20:23]
	v_mfma_f32_16x16x32_bf16 v[8:11], v[148:151], v[228:231], v[8:11]
	v_mfma_f32_16x16x32_bf16 v[4:7], v[164:167], v[228:231], v[4:7]
	v_mfma_f32_16x16x32_bf16 v[56:59], v[160:163], v[196:199], v[56:59]
	v_mfma_f32_16x16x32_bf16 v[52:55], v[188:191], v[196:199], v[52:55]
	v_mfma_f32_16x16x32_bf16 v[40:43], v[160:163], v[216:219], v[40:43]
	v_mfma_f32_16x16x32_bf16 v[36:39], v[188:191], v[216:219], v[36:39]
	v_mfma_f32_16x16x32_bf16 v[24:27], v[160:163], v[224:227], v[24:27]
	v_mfma_f32_16x16x32_bf16 v[20:23], v[188:191], v[224:227], v[20:23]
	v_mfma_f32_16x16x32_bf16 v[8:11], v[160:163], v[232:235], v[8:11]
	v_mfma_f32_16x16x32_bf16 v[4:7], v[188:191], v[232:235], v[4:7]
	s_setprio 0
	s_barrier
	s_add_i32 s53, s53, 2
	s_add_u32 s36, s36, 0x100
	s_addc_u32 s37, s37, 0
	s_cmpk_gt_u32 s53, 0x55
	s_mov_b64 s[20:21], s[22:23]
	s_cbranch_scc0 .LBB0_863
	s_and_b64 vcc, exec, s[6:7]
	s_cbranch_vccz .LBB0_866
	s_barrier

; __global__ void __launch_bounds__(512, 2) fwd_kernel(Args a) {
	.amdhsa_kernel _Z10fwd_kernel4Args
		.amdhsa_group_segment_fixed_size 0
		.amdhsa_private_segment_fixed_size 0
		.amdhsa_kernarg_size 440
		.amdhsa_user_sgpr_count 2
		.amdhsa_user_sgpr_dispatch_ptr 0
		.amdhsa_user_sgpr_queue_ptr 0
		.amdhsa_user_sgpr_kernarg_segment_ptr 1
		.amdhsa_user_sgpr_dispatch_id 0
		.amdhsa_user_sgpr_kernarg_preload_length 0
		.amdhsa_user_sgpr_kernarg_preload_offset 0
		.amdhsa_user_sgpr_private_segment_size 0
		.amdhsa_uses_dynamic_stack 0
		.amdhsa_enable_private_segment 0
		.amdhsa_system_sgpr_workgroup_id_x 1
		.amdhsa_system_sgpr_workgroup_id_y 0
		.amdhsa_system_sgpr_workgroup_id_z 0
		.amdhsa_system_sgpr_workgroup_info 0
		.amdhsa_system_vgpr_workitem_id 2
		.amdhsa_next_free_vgpr 255
		.amdhsa_next_free_sgpr 102
		.amdhsa_accum_offset 256
		.amdhsa_reserve_vcc 1
		.amdhsa_float_round_mode_32 0
		.amdhsa_float_round_mode_16_64 0
		.amdhsa_float_denorm_mode_32 3
		.amdhsa_float_denorm_mode_16_64 3
		.amdhsa_dx10_clamp 1
		.amdhsa_ieee_mode 1
		.amdhsa_fp16_overflow 0
		.amdhsa_tg_split 0
		.amdhsa_exception_fp_ieee_invalid_op 0
		.amdhsa_exception_fp_denorm_src 0
		.amdhsa_exception_fp_ieee_div_zero 0
		.amdhsa_exception_fp_ieee_overflow 0
		.amdhsa_exception_fp_ieee_underflow 0
		.amdhsa_exception_fp_ieee_inexact 0
		.amdhsa_exception_int_div_zero 0
	.end_amdhsa_kernel

; __global__ void __launch_bounds__(512, 2) fwd_kernel(Args a) {
amdhsa.kernels:
  - .agpr_count:     0
    .args:
      - .offset:         0
        .size:           184
        .value_kind:     by_value
      - .offset:         184
        .size:           4
        .value_kind:     hidden_block_count_x
      - .offset:         188
        .size:           4
        .value_kind:     hidden_block_count_y
      - .offset:         192
        .size:           4
        .value_kind:     hidden_block_count_z
      - .offset:         196
        .size:           2
        .value_kind:     hidden_group_size_x
      - .offset:         198
        .size:           2
        .value_kind:     hidden_group_size_y
      - .offset:         200
        .size:           2
        .value_kind:     hidden_group_size_z
      - .offset:         202
        .size:           2
        .value_kind:     hidden_remainder_x
      - .offset:         204
        .size:           2
        .value_kind:     hidden_remainder_y
      - .offset:         206
        .size:           2
        .value_kind:     hidden_remainder_z
      - .offset:         224
        .size:           8
        .value_kind:     hidden_global_offset_x
      - .offset:         232
        .size:           8
        .value_kind:     hidden_global_offset_y
      - .offset:         240
        .size:           8
        .value_kind:     hidden_global_offset_z
      - .offset:         248
        .size:           2
        .value_kind:     hidden_grid_dims
      - .offset:         272
        .size:           8
        .value_kind:     hidden_multigrid_sync_arg
      - .offset:         304
        .size:           4
        .value_kind:     hidden_dynamic_lds_size
    .group_segment_fixed_size: 0
    .kernarg_segment_align: 8
    .kernarg_segment_size: 440
    .language:       OpenCL C
    .language_version:
      - 2
      - 0
    .max_flat_workgroup_size: 512
    .name:           _Z10fwd_kernel4Args
    .private_segment_fixed_size: 0
    .sgpr_count:     108
    .sgpr_spill_count: 154
    .symbol:         _Z10fwd_kernel4Args.kd
    .uniform_work_group_size: 1
    .uses_dynamic_stack: false
    .vgpr_count:     255
    .vgpr_spill_count: 0
    .wavefront_size: 64
